# SSD1 conv staging: 11 more row loads issued with the first two before the first wait (same de-serialisation as SSD3), counted waits re-derived
# baseline (speedup 1.0000x reference)
; template <bool WITH_C, bool B_TR>
; __device__ __forceinline__ void ssd_stage(const Params& p, LAS unsigned char* lds, int b, int c, int g) {
;     ...
;         const int tb = 64 * c + 16 * seg;
;         const bf16_t* src = (const bf16_t*)(p.ws + WS_XBC) + ((size_t)b * SEQ + tb) * D_XBC + col0;
;         const u32x4 zz = {0u, 0u, 0u, 0u};
;         u32x4 rows[19];
;         rows[0] = tb >= 3 ? *(const u32x4*)(src - 3 * D_XBC) : zz; rows[1] = tb >= 2 ? *(const u32x4*)(src - 2 * D_XBC) : zz; rows[2] = tb >= 1 ? *(const u32x4*)(src - 1 * D_XBC) : zz;
; #pragma unroll
;         for (int tt = 0; tt < 16; ++tt) rows[3 + tt] = *(const u32x4*)(src + (size_t)tt * D_XBC);
;         float u1[8], u2[8], u3[8];
;         unpack8(rows[0], u3); unpack8(rows[1], u2); unpack8(rows[2], u1);
; #pragma unroll
;         for (int hb = 0; hb < 2; ++hb) {
;             float y[8][8];
; #pragma unroll
;             for (int tt = 0; tt < 8; ++tt) {
;                 float u0[8]; unpack8(rows[3 + 8 * hb + tt], u0);
; #pragma unroll
;                 for (int i = 0; i < 8; ++i) { const float a = w0[i] * u3[i] + w1[i] * u2[i] + w2[i] * u1[i] + w3[i] * u0[i] + bs[i]; y[tt][i] = a * __builtin_amdgcn_rcpf(1.f + __expf(-a)); u3[i] = u2[i]; u2[i] = u1[i]; u1[i] = u0[i]; }
.LBB0_565:
	s_or_b64 exec, exec, s[24:25]
	v_add_co_u32_e32 v26, vcc, s27, v24
	v_cndmask_b32_e64 v117, v179, 0, s[2:3]
	s_nop 0
	v_addc_co_u32_e32 v27, vcc, 0, v25, vcc
	global_load_dwordx4 v[100:103], v[24:25], off
	global_load_dwordx4 v[76:79], v[26:27], off offset:2048
	s_mov_b32 s101, 0
	s_movk_i32 s100, 0x3000
	v_lshl_add_u64 v[26:27], v[24:25], 0, s[100:101]
	global_load_dwordx4 v[80:83], v[26:27], off
	s_movk_i32 s100, 0x4000
	v_lshl_add_u64 v[26:27], v[24:25], 0, s[100:101]
	global_load_dwordx4 v[68:71], v[26:27], off offset:2048
	s_movk_i32 s100, 0x6000
	v_lshl_add_u64 v[26:27], v[24:25], 0, s[100:101]
	global_load_dwordx4 v[72:75], v[26:27], off
	s_movk_i32 s100, 0x7000
	v_lshl_add_u64 v[26:27], v[24:25], 0, s[100:101]
	global_load_dwordx4 v[60:63], v[26:27], off offset:2048
	s_mov_b32 s100, 0x9000
	v_lshl_add_u64 v[26:27], v[24:25], 0, s[100:101]
	global_load_dwordx4 v[64:67], v[26:27], off
	s_mov_b32 s100, 0xa000
	v_lshl_add_u64 v[26:27], v[24:25], 0, s[100:101]
	global_load_dwordx4 v[52:55], v[26:27], off offset:2048
	s_mov_b32 s100, 0xc000
	v_lshl_add_u64 v[26:27], v[24:25], 0, s[100:101]
	global_load_dwordx4 v[56:59], v[26:27], off
	s_mov_b32 s100, 0xd000
	v_lshl_add_u64 v[26:27], v[24:25], 0, s[100:101]
	global_load_dwordx4 v[44:47], v[26:27], off offset:2048
	s_mov_b32 s100, 0xf000
	v_lshl_add_u64 v[26:27], v[24:25], 0, s[100:101]
	global_load_dwordx4 v[48:51], v[26:27], off
	s_mov_b32 s100, 0x10000
	v_lshl_add_u64 v[26:27], v[24:25], 0, s[100:101]
	global_load_dwordx4 v[36:39], v[26:27], off offset:2048
	s_mov_b32 s100, 0x12000
	v_lshl_add_u64 v[26:27], v[24:25], 0, s[100:101]
	global_load_dwordx4 v[40:43], v[26:27], off
	v_add_u32_e32 v185, 0, v117
	v_add_u32_e32 v117, 0x7ffffe00, v116
	s_waitcnt vmcnt(13)
	v_lshlrev_b32_e32 v121, 16, v112
	v_lshlrev_b32_e32 v120, 16, v108
	v_mov_b32_e32 v118, v104
	v_mov_b32_e32 v119, v12
	v_cndmask_b32_e64 v186, v117, v116, s[2:3]
	v_pk_mul_f32 v[122:123], v[118:119], v[120:121]
	v_mov_b32_e32 v116, v106
	v_mov_b32_e32 v117, v14
	v_mov_b32_e32 v14, v107
	v_lshlrev_b32_e32 v202, 16, v92
	v_mov_b32_e32 v106, v88
	v_mov_b32_e32 v107, v20
	v_mov_b32_e32 v12, v105
	v_mov_b32_e32 v105, v0
	v_mov_b32_e32 v0, v97
	v_mov_b32_e32 v97, v2
	v_add_f32_e32 v2, v122, v123
	v_and_b32_e32 v125, 0xffff0000, v112
	v_and_b32_e32 v124, 0xffff0000, v108
	v_pk_mul_f32 v[126:127], v[12:13], v[124:125]
	v_lshlrev_b32_e32 v133, 16, v114
	v_lshlrev_b32_e32 v132, 16, v110
	v_and_b32_e32 v193, 0xffff0000, v114
	v_and_b32_e32 v192, 0xffff0000, v110
	v_lshlrev_b32_e32 v198, 16, v111
	v_and_b32_e32 v114, 0xffff0000, v111
	v_and_b32_e32 v110, 0xffff0000, v92
	v_add_f32_e32 v92, v126, v127
	v_add_co_u32_e32 v26, vcc, s26, v24
	s_movk_i32 s4, 0x4000
	s_nop 0
	v_addc_co_u32_e32 v27, vcc, 0, v25, vcc
	v_add_co_u32_e32 v28, vcc, s4, v24
	v_lshlrev_b32_e32 v128, 16, v109
	s_nop 0
	v_addc_co_u32_e32 v29, vcc, 0, v25, vcc
	s_nop 0
	s_nop 0
	v_lshlrev_b32_e32 v129, 16, v113
	v_pk_mul_f32 v[130:131], v[116:117], v[128:129]
	v_and_b32_e32 v113, 0xffff0000, v113
	v_and_b32_e32 v112, 0xffff0000, v109
	v_pk_mul_f32 v[108:109], v[14:15], v[112:113]
	v_mov_b32_e32 v104, v96
	v_pk_mul_f32 v[134:135], v[104:105], v[132:133]
	v_pk_mul_f32 v[196:197], v[0:1], v[192:193]
	v_and_b32_e32 v210, 0xffff0000, v94
	v_lshlrev_b32_e32 v199, 16, v115
	v_mov_b32_e32 v96, v98
	v_pk_mul_f32 v[200:201], v[96:97], v[198:199]
	v_and_b32_e32 v115, 0xffff0000, v115
	v_and_b32_e32 v212, 0xffff0000, v95
	s_movk_i32 s4, 0x6000
	v_add_co_u32_e32 v26, vcc, s4, v24
	s_movk_i32 s4, 0x7000
	s_nop 0
	v_addc_co_u32_e32 v27, vcc, 0, v25, vcc
	v_add_co_u32_e32 v28, vcc, s4, v24
	s_mov_b32 s4, 0x9000
	s_nop 0
	v_addc_co_u32_e32 v29, vcc, 0, v25, vcc
	s_nop 0
	s_nop 0
	v_add_co_u32_e32 v26, vcc, s4, v24
	s_mov_b32 s4, 0xa000
	s_nop 0
	v_addc_co_u32_e32 v27, vcc, 0, v25, vcc
	v_add_co_u32_e32 v28, vcc, s4, v24
	s_mov_b32 s4, 0xc000
	s_nop 0
	v_addc_co_u32_e32 v29, vcc, 0, v25, vcc
	s_nop 0
	s_nop 0
	s_waitcnt vmcnt(12)
	v_lshlrev_b32_e32 v203, 16, v100
	v_pk_mul_f32 v[188:189], v[106:107], v[202:203]
	v_and_b32_e32 v111, 0xffff0000, v100
	v_add_f32_e32 v2, v2, v188
	v_add_f32_e32 v2, v2, v189
	v_add_f32_e32 v120, v16, v2
	v_mul_f32_e32 v2, 0xbfb8aa3b, v120
	v_exp_f32_e32 v20, v2
	v_lshlrev_b32_e32 v123, 16, v101
	v_and_b32_e32 v101, 0xffff0000, v101
	v_pk_mov_b32 v[124:125], v[124:125], v[110:111] op_sel:[1,0]
	v_add_f32_e32 v20, 1.0, v20
	v_rcp_f32_e32 v122, v20
	v_mov_b32_e32 v20, v89
	v_pk_mul_f32 v[88:89], v[20:21], v[110:111]
	v_and_b32_e32 v211, 0xffff0000, v102
	v_add_f32_e32 v88, v92, v88
	v_add_f32_e32 v88, v88, v89
	v_add_f32_e32 v92, v17, v88
	v_mul_f32_e32 v88, 0xbfb8aa3b, v92
	v_exp_f32_e32 v100, v88
	v_pk_mov_b32 v[88:89], v[120:121], v[202:203] op_sel:[1,0]
	v_mul_f32_e32 v191, v120, v122
	v_pk_mul_f32 v[120:121], v[118:119], v[88:89]
	v_add_f32_e32 v88, 1.0, v100
	v_rcp_f32_e32 v100, v88
	v_lshlrev_b32_e32 v122, 16, v93
	v_mov_b32_e32 v88, v90
	v_mov_b32_e32 v89, v22
	v_pk_mul_f32 v[126:127], v[88:89], v[122:123]
	v_add_f32_e32 v22, v130, v131
	v_add_f32_e32 v22, v22, v126
	v_add_f32_e32 v22, v22, v127
	v_add_f32_e32 v128, v18, v22
	v_mul_f32_e32 v22, 0xbfb8aa3b, v128
	v_exp_f32_e32 v22, v22
	v_mul_f32_e32 v190, v92, v100
	v_and_b32_e32 v100, 0xffff0000, v93
	v_add_f32_e32 v92, v108, v109
	v_add_f32_e32 v22, 1.0, v22
	v_rcp_f32_e32 v130, v22
	v_mov_b32_e32 v22, v91
	v_pk_mul_f32 v[90:91], v[22:23], v[100:101]
	v_mov_b32_e32 v2, v99
	v_add_f32_e32 v90, v92, v90
	v_add_f32_e32 v90, v90, v91
	v_add_f32_e32 v131, v19, v90
	v_mul_f32_e32 v90, 0xbfb8aa3b, v131
	v_exp_f32_e32 v90, v90
	v_mul_f32_e32 v189, v128, v130
	v_pk_mul_f32 v[92:93], v[12:13], v[124:125]
; template <bool WITH_C, bool B_TR>
; __device__ __forceinline__ void ssd_stage(const Params& p, LAS unsigned char* lds, int b, int c, int g) {
;     ...
;         for (int hb = 0; hb < 2; ++hb) {
;             float y[8][8];
; #pragma unroll
;             for (int tt = 0; tt < 8; ++tt) {
;                 float u0[8]; unpack8(rows[3 + 8 * hb + tt], u0);
; #pragma unroll
;                 for (int i = 0; i < 8; ++i) { const float a = w0[i] * u3[i] + w1[i] * u2[i] + w2[i] * u1[i] + w3[i] * u0[i] + bs[i]; y[tt][i] = a * __builtin_amdgcn_rcpf(1.f + __expf(-a)); u3[i] = u2[i]; u2[i] = u1[i]; u1[i] = u0[i]; }
	v_pk_mul_f32 v[98:99], v[2:3], v[114:115]
	v_add_f32_e32 v90, 1.0, v90
	v_rcp_f32_e32 v130, v90
	v_pk_mov_b32 v[90:91], v[128:129], v[122:123] op_sel:[1,0]
	v_and_b32_e32 v213, 0xffff0000, v103
	v_pk_mul_f32 v[124:125], v[116:117], v[90:91]
	v_mul_f32_e32 v188, v131, v130
	v_lshlrev_b32_e32 v130, 16, v94
	v_lshlrev_b32_e32 v131, 16, v102
	v_mov_b32_e32 v90, v84
	v_mov_b32_e32 v91, v8
	v_pk_mul_f32 v[204:205], v[90:91], v[130:131]
	v_add_f32_e32 v8, v134, v135
	v_add_f32_e32 v8, v8, v204
	v_add_f32_e32 v8, v8, v205
	v_add_f32_e32 v132, v4, v8
	v_mul_f32_e32 v8, 0xbfb8aa3b, v132
	v_exp_f32_e32 v8, v8
	v_add_f32_e32 v94, v196, v197
	v_lshlrev_b32_e32 v196, 16, v95
	v_lshlrev_b32_e32 v197, 16, v103
	v_add_f32_e32 v8, 1.0, v8
	v_rcp_f32_e32 v139, v8
	v_mov_b32_e32 v8, v85
	v_pk_mul_f32 v[84:85], v[8:9], v[210:211]
	v_add_f32_e32 v95, v98, v99
	v_add_f32_e32 v84, v94, v84
	v_add_f32_e32 v84, v84, v85
	v_add_f32_e32 v94, v5, v84
	v_mul_f32_e32 v84, 0xbfb8aa3b, v94
	v_exp_f32_e32 v102, v84
	v_pk_mov_b32 v[84:85], v[132:133], v[130:131] op_sel:[1,0]
	v_mul_f32_e32 v187, v132, v139
	v_pk_mul_f32 v[132:133], v[104:105], v[84:85]
	v_add_f32_e32 v84, 1.0, v102
	v_rcp_f32_e32 v102, v84
	v_mov_b32_e32 v84, v86
	v_mov_b32_e32 v85, v10
	v_pk_mul_f32 v[204:205], v[84:85], v[196:197]
	v_add_f32_e32 v10, v200, v201
	v_add_f32_e32 v10, v10, v204
	v_add_f32_e32 v10, v10, v205
	v_add_f32_e32 v139, v6, v10
	v_mul_f32_e32 v10, 0xbfb8aa3b, v139
	v_exp_f32_e32 v10, v10
	v_mul_f32_e32 v184, v94, v102
	v_add_f32_e32 v120, v120, v121
	v_pk_mul_f32 v[126:127], v[118:119], v[202:203]
	v_add_f32_e32 v10, 1.0, v10
	v_rcp_f32_e32 v94, v10
	v_mov_b32_e32 v10, v87
	v_pk_mul_f32 v[86:87], v[10:11], v[212:213]
	v_add_f32_e32 v126, v126, v127
	v_add_f32_e32 v86, v95, v86
	v_add_f32_e32 v86, v86, v87
	v_add_f32_e32 v95, v7, v86
	v_mul_f32_e32 v86, 0xbfb8aa3b, v95
	v_exp_f32_e32 v86, v86
	v_mul_f32_e32 v183, v139, v94
	v_pk_mul_f32 v[108:109], v[12:13], v[110:111]
	v_pk_mul_f32 v[128:129], v[116:117], v[122:123]
	v_add_f32_e32 v86, 1.0, v86
	v_rcp_f32_e32 v94, v86
	v_pk_mov_b32 v[86:87], v[198:199], v[196:197] op_sel:[1,0]
	v_pk_mov_b32 v[112:113], v[112:113], v[100:101] op_sel:[1,0]
	v_pk_mul_f32 v[214:215], v[96:97], v[86:87]
	v_mul_f32_e32 v139, v95, v94
	s_waitcnt vmcnt(10)
	v_lshlrev_b32_e32 v95, 16, v80
	v_lshlrev_b32_e32 v94, 16, v76
	v_pk_mov_b32 v[86:87], v[114:115], v[212:213] op_sel:[1,0]
	v_pk_mov_b32 v[114:115], v[202:203], v[94:95] op_sel:[1,0]
	v_pk_mul_f32 v[218:219], v[2:3], v[86:87]
	v_pk_mul_f32 v[102:103], v[106:107], v[114:115]
	v_pk_mul_f32 v[222:223], v[118:119], v[114:115]
	v_add_f32_e32 v102, v120, v102
	v_add_f32_e32 v102, v102, v103
	v_add_f32_e32 v120, v16, v102
	v_mul_f32_e32 v102, 0xbfb8aa3b, v120
	v_exp_f32_e32 v121, v102
	v_pk_mul_f32 v[102:103], v[106:107], v[94:95]
	v_add_f32_e32 v115, v128, v129
	v_add_f32_e32 v102, v126, v102
	v_add_f32_e32 v102, v102, v103
	v_add_f32_e32 v126, v16, v102
	v_mul_f32_e32 v102, 0xbfb8aa3b, v126
	v_exp_f32_e32 v102, v102
	v_add_f32_e32 v86, 1.0, v121
	v_rcp_f32_e32 v121, v86
	v_and_b32_e32 v103, 0xffff0000, v80
	v_add_f32_e32 v86, 1.0, v102
	v_and_b32_e32 v102, 0xffff0000, v76
	v_pk_mov_b32 v[110:111], v[110:111], v[102:103] op_sel:[1,0]
	v_rcp_f32_e32 v127, v86
	v_pk_mul_f32 v[86:87], v[20:21], v[110:111]
	v_add_f32_e32 v76, v92, v93
	v_add_f32_e32 v76, v76, v86
	v_add_f32_e32 v76, v76, v87
	v_add_f32_e32 v76, v17, v76
	v_mul_f32_e32 v80, 0xbfb8aa3b, v76
	v_exp_f32_e32 v80, v80
	v_pk_mul_f32 v[86:87], v[20:21], v[102:103]
	v_add_f32_e32 v92, v108, v109
	v_add_f32_e32 v86, v92, v86
	v_add_f32_e32 v86, v86, v87
	v_mul_f32_e32 v208, v120, v121
	v_add_f32_e32 v120, v17, v86
	v_add_f32_e32 v80, 1.0, v80
	v_mul_f32_e32 v86, 0xbfb8aa3b, v120
	v_rcp_f32_e32 v80, v80
	v_exp_f32_e32 v86, v86
	v_lshlrev_b32_e32 v87, 16, v81
	v_and_b32_e32 v121, 0xffff0000, v81
	v_mul_f32_e32 v206, v76, v80
	v_add_f32_e32 v76, 1.0, v86
	v_lshlrev_b32_e32 v86, 16, v77
	v_pk_mov_b32 v[92:93], v[122:123], v[86:87] op_sel:[1,0]
	v_add_f32_e32 v80, v124, v125
	v_pk_mul_f32 v[108:109], v[88:89], v[92:93]
	v_rcp_f32_e32 v76, v76
	v_add_f32_e32 v80, v80, v108
	v_add_f32_e32 v80, v80, v109
	v_add_f32_e32 v80, v18, v80
	v_mul_f32_e32 v108, 0xbfb8aa3b, v80
	v_exp_f32_e32 v114, v108
	v_pk_mul_f32 v[108:109], v[88:89], v[86:87]
	v_mul_f32_e32 v207, v120, v76
	v_add_f32_e32 v108, v115, v108
	v_add_f32_e32 v108, v108, v109
	v_add_f32_e32 v108, v18, v108
	v_add_f32_e32 v76, 1.0, v114
	v_mul_f32_e32 v109, 0xbfb8aa3b, v108
	v_rcp_f32_e32 v76, v76
	v_exp_f32_e32 v109, v109
	v_and_b32_e32 v120, 0xffff0000, v77
	v_pk_mul_f32 v[112:113], v[14:15], v[112:113]
	v_mul_f32_e32 v204, v80, v76
	v_pk_mov_b32 v[76:77], v[100:101], v[120:121] op_sel:[1,0]
	v_pk_mul_f32 v[134:135], v[14:15], v[100:101]
	v_add_f32_e32 v109, 1.0, v109
	v_pk_mul_f32 v[80:81], v[22:23], v[76:77]
	v_add_f32_e32 v100, v112, v113
	v_rcp_f32_e32 v109, v109
	v_add_f32_e32 v80, v100, v80
	v_add_f32_e32 v80, v80, v81
	v_add_f32_e32 v100, v19, v80
	v_mul_f32_e32 v80, 0xbfb8aa3b, v100
	v_mul_f32_e32 v199, v108, v109
	v_exp_f32_e32 v101, v80
	v_pk_mul_f32 v[80:81], v[22:23], v[120:121]
	v_add_f32_e32 v108, v134, v135
	v_add_f32_e32 v80, v108, v80
	v_add_f32_e32 v80, v80, v81
	v_add_f32_e32 v108, v19, v80
	v_mul_f32_e32 v80, 0xbfb8aa3b, v108
	v_exp_f32_e32 v80, v80
	v_add_f32_e32 v81, 1.0, v101
	v_lshlrev_b32_e32 v113, 16, v82
	v_lshlrev_b32_e32 v112, 16, v78
	v_add_f32_e32 v80, 1.0, v80
	v_rcp_f32_e32 v101, v81
	v_rcp_f32_e32 v109, v80
	v_pk_mov_b32 v[80:81], v[130:131], v[112:113] op_sel:[1,0]
	v_pk_mul_f32 v[226:227], v[12:13], v[110:111]
	v_pk_mul_f32 v[124:125], v[116:117], v[92:93]
; template <bool WITH_C, bool B_TR>
; __device__ __forceinline__ void ssd_stage(const Params& p, LAS unsigned char* lds, int b, int c, int g) {
;     ...
;         for (int hb = 0; hb < 2; ++hb) {
;             float y[8][8];
; #pragma unroll
;             for (int tt = 0; tt < 8; ++tt) {
;                 float u0[8]; unpack8(rows[3 + 8 * hb + tt], u0);
; #pragma unroll
;                 for (int i = 0; i < 8; ++i) { const float a = w0[i] * u3[i] + w1[i] * u2[i] + w2[i] * u1[i] + w3[i] * u0[i] + bs[i]; y[tt][i] = a * __builtin_amdgcn_rcpf(1.f + __expf(-a)); u3[i] = u2[i]; u2[i] = u1[i]; u1[i] = u0[i]; }
	v_pk_mul_f32 v[92:93], v[90:91], v[80:81]
	v_add_f32_e32 v110, v132, v133
	v_add_f32_e32 v92, v110, v92
	v_add_f32_e32 v92, v92, v93
	v_add_f32_e32 v110, v4, v92
	v_mul_f32_e32 v92, 0xbfb8aa3b, v110
	v_exp_f32_e32 v92, v92
	v_pk_mul_f32 v[200:201], v[104:105], v[130:131]
	v_mul_f32_e32 v205, v100, v101
	v_add_f32_e32 v101, v200, v201
	v_add_f32_e32 v92, 1.0, v92
	v_rcp_f32_e32 v100, v92
	v_pk_mul_f32 v[92:93], v[90:91], v[112:113]
	v_mul_f32_e32 v203, v108, v109
	v_add_f32_e32 v92, v101, v92
	v_add_f32_e32 v92, v92, v93
	v_add_f32_e32 v108, v4, v92
	v_mul_f32_e32 v92, 0xbfb8aa3b, v108
	v_exp_f32_e32 v92, v92
	v_pk_mov_b32 v[192:193], v[192:193], v[210:211] op_sel:[1,0]
	v_pk_mul_f32 v[132:133], v[14:15], v[76:77]
	v_mul_f32_e32 v201, v110, v100
	v_add_f32_e32 v76, 1.0, v92
	v_and_b32_e32 v101, 0xffff0000, v82
	v_and_b32_e32 v100, 0xffff0000, v78
	v_pk_mul_f32 v[98:99], v[0:1], v[192:193]
	v_rcp_f32_e32 v109, v76
	v_pk_mov_b32 v[76:77], v[210:211], v[100:101] op_sel:[1,0]
	v_add_f32_e32 v78, v98, v99
	v_pk_mul_f32 v[92:93], v[8:9], v[76:77]
	v_pk_mul_f32 v[192:193], v[0:1], v[210:211]
	v_add_f32_e32 v78, v78, v92
	v_add_f32_e32 v78, v78, v93
	v_pk_mul_f32 v[92:93], v[8:9], v[100:101]
	v_add_f32_e32 v98, v192, v193
	v_add_f32_e32 v92, v98, v92
	v_add_f32_e32 v92, v92, v93
	v_add_f32_e32 v92, v5, v92
	v_mul_f32_e32 v93, 0xbfb8aa3b, v92
	v_add_f32_e32 v78, v5, v78
	v_exp_f32_e32 v93, v93
	v_mul_f32_e32 v82, 0xbfb8aa3b, v78
	v_exp_f32_e32 v82, v82
	v_pk_mul_f32 v[128:129], v[104:105], v[80:81]
	v_add_f32_e32 v93, 1.0, v93
	v_rcp_f32_e32 v93, v93
	v_add_f32_e32 v82, 1.0, v82
	v_rcp_f32_e32 v82, v82
	v_pk_mul_f32 v[216:217], v[96:97], v[196:197]
	v_mul_f32_e32 v193, v92, v93
	v_lshlrev_b32_e32 v93, 16, v83
	v_lshlrev_b32_e32 v92, 16, v79
	v_pk_mov_b32 v[98:99], v[196:197], v[92:93] op_sel:[1,0]
	v_mul_f32_e32 v198, v78, v82
	v_pk_mul_f32 v[80:81], v[84:85], v[98:99]
	v_add_f32_e32 v78, v214, v215
	v_add_f32_e32 v78, v78, v80
	v_mul_f32_e32 v202, v108, v109
	v_add_f32_e32 v78, v78, v81
	v_pk_mul_f32 v[80:81], v[84:85], v[92:93]
	v_add_f32_e32 v108, v216, v217
	v_add_f32_e32 v80, v108, v80
	v_add_f32_e32 v82, v6, v78
	v_add_f32_e32 v80, v80, v81
	v_mul_f32_e32 v78, 0xbfb8aa3b, v82
	v_add_f32_e32 v108, v6, v80
	v_exp_f32_e32 v78, v78
	v_mul_f32_e32 v80, 0xbfb8aa3b, v108
	v_exp_f32_e32 v80, v80
	v_pk_mul_f32 v[114:115], v[0:1], v[76:77]
	v_add_f32_e32 v76, 1.0, v78
	v_rcp_f32_e32 v109, v76
	v_add_f32_e32 v76, 1.0, v80
	v_and_b32_e32 v81, 0xffff0000, v83
	v_and_b32_e32 v80, 0xffff0000, v79
	v_rcp_f32_e32 v110, v76
	v_pk_mov_b32 v[76:77], v[212:213], v[80:81] op_sel:[1,0]
	v_add_f32_e32 v83, v218, v219
	v_pk_mul_f32 v[78:79], v[10:11], v[76:77]
	v_pk_mul_f32 v[220:221], v[2:3], v[212:213]
	v_add_f32_e32 v78, v83, v78
	v_add_f32_e32 v78, v78, v79
	v_add_f32_e32 v83, v7, v78
	v_mul_f32_e32 v78, 0xbfb8aa3b, v83
	v_exp_f32_e32 v78, v78
	v_mul_f32_e32 v200, v82, v109
	v_mul_f32_e32 v197, v108, v110
	v_add_f32_e32 v108, v220, v221
	v_add_f32_e32 v78, 1.0, v78
	v_rcp_f32_e32 v82, v78
	v_pk_mul_f32 v[78:79], v[10:11], v[80:81]
	v_pk_mul_f32 v[110:111], v[96:97], v[98:99]
	v_add_f32_e32 v78, v108, v78
	v_add_f32_e32 v78, v78, v79
	v_add_f32_e32 v192, v7, v78
	v_mul_f32_e32 v78, 0xbfb8aa3b, v192
	v_exp_f32_e32 v78, v78
	s_waitcnt vmcnt(8)
	v_lshlrev_b32_e32 v79, 16, v72
	v_mul_f32_e32 v196, v83, v82
	v_pk_mul_f32 v[224:225], v[118:119], v[94:95]
	v_add_f32_e32 v78, 1.0, v78
	v_rcp_f32_e32 v98, v78
	v_lshlrev_b32_e32 v78, 16, v68
	v_pk_mov_b32 v[82:83], v[94:95], v[78:79] op_sel:[1,0]
	v_add_f32_e32 v99, v222, v223
	v_pk_mul_f32 v[94:95], v[106:107], v[82:83]
	v_mul_f32_e32 v192, v192, v98
	v_add_f32_e32 v94, v99, v94
	v_add_f32_e32 v94, v94, v95
	v_add_f32_e32 v195, v16, v94
	v_mul_f32_e32 v94, 0xbfb8aa3b, v195
	v_exp_f32_e32 v210, v94
	v_pk_mul_f32 v[98:99], v[2:3], v[76:77]
	v_pk_mul_f32 v[228:229], v[12:13], v[102:103]
	v_pk_mul_f32 v[134:135], v[116:117], v[86:87]
	v_add_f32_e32 v76, 1.0, v210
	v_rcp_f32_e32 v214, v76
	v_pk_mul_f32 v[76:77], v[106:107], v[78:79]
	v_add_f32_e32 v210, v224, v225
	v_add_f32_e32 v76, v210, v76
	v_add_f32_e32 v76, v76, v77
	v_add_f32_e32 v215, v16, v76
	v_mul_f32_e32 v76, 0xbfb8aa3b, v215
	v_exp_f32_e32 v216, v76
	s_waitcnt vmcnt(6)
	v_lshlrev_b32_e32 v77, 16, v64
	v_lshlrev_b32_e32 v76, 16, v60
	v_pk_mul_f32 v[210:211], v[118:119], v[82:83]
	v_pk_mov_b32 v[82:83], v[78:79], v[76:77] op_sel:[1,0]
	v_add_f32_e32 v210, v210, v211
	v_pk_mul_f32 v[212:213], v[106:107], v[82:83]
	v_add_f32_e32 v211, 1.0, v216
	v_add_f32_e32 v210, v210, v212
	v_add_f32_e32 v210, v210, v213
	v_add_f32_e32 v212, v16, v210
	v_mul_f32_e32 v210, 0xbfb8aa3b, v212
	v_exp_f32_e32 v210, v210
	v_pk_mul_f32 v[78:79], v[118:119], v[78:79]
	v_rcp_f32_e32 v213, v211
	v_add_f32_e32 v78, v78, v79
	v_add_f32_e32 v210, 1.0, v210
	v_rcp_f32_e32 v216, v210
	v_pk_mul_f32 v[210:211], v[106:107], v[76:77]
	v_mul_f32_e32 v218, v215, v213
	v_add_f32_e32 v78, v78, v210
	v_add_f32_e32 v78, v78, v211
	v_add_f32_e32 v217, v16, v78
	v_mul_f32_e32 v78, 0xbfb8aa3b, v217
	v_exp_f32_e32 v78, v78
	v_and_b32_e32 v211, 0xffff0000, v72
	v_and_b32_e32 v210, 0xffff0000, v68
	v_mul_f32_e32 v216, v212, v216
	v_add_f32_e32 v78, 1.0, v78
	v_rcp_f32_e32 v212, v78
	v_pk_mov_b32 v[78:79], v[102:103], v[210:211] op_sel:[1,0]
	v_add_f32_e32 v68, v226, v227
	v_pk_mul_f32 v[102:103], v[20:21], v[78:79]
	v_add_f32_e32 v213, v228, v229
	v_add_f32_e32 v68, v68, v102
	v_add_f32_e32 v68, v68, v103
	v_pk_mul_f32 v[102:103], v[20:21], v[210:211]
	v_add_f32_e32 v68, v17, v68
	v_add_f32_e32 v102, v213, v102
	v_mul_f32_e32 v72, 0xbfb8aa3b, v68
	v_add_f32_e32 v102, v102, v103
	v_exp_f32_e32 v72, v72
; template <bool WITH_C, bool B_TR>
; __device__ __forceinline__ void ssd_stage(const Params& p, LAS unsigned char* lds, int b, int c, int g) {
;     ...
;         for (int hb = 0; hb < 2; ++hb) {
;             float y[8][8];
; #pragma unroll
;             for (int tt = 0; tt < 8; ++tt) {
;                 float u0[8]; unpack8(rows[3 + 8 * hb + tt], u0);
; #pragma unroll
;                 for (int i = 0; i < 8; ++i) { const float a = w0[i] * u3[i] + w1[i] * u2[i] + w2[i] * u1[i] + w3[i] * u0[i] + bs[i]; y[tt][i] = a * __builtin_amdgcn_rcpf(1.f + __expf(-a)); u3[i] = u2[i]; u2[i] = u1[i]; u1[i] = u0[i]; }
	v_add_f32_e32 v219, v17, v102
	v_mul_f32_e32 v102, 0xbfb8aa3b, v219
	v_exp_f32_e32 v102, v102
	v_add_f32_e32 v72, 1.0, v72
	v_rcp_f32_e32 v72, v72
	v_mul_f32_e32 v217, v217, v212
	v_add_f32_e32 v102, 1.0, v102
	v_pk_mul_f32 v[212:213], v[12:13], v[78:79]
	v_and_b32_e32 v79, 0xffff0000, v64
	v_and_b32_e32 v78, 0xffff0000, v60
	v_rcp_f32_e32 v220, v102
	v_pk_mov_b32 v[102:103], v[210:211], v[78:79] op_sel:[1,0]
	v_mul_f32_e32 v195, v195, v214
	v_pk_mul_f32 v[214:215], v[20:21], v[102:103]
	v_add_f32_e32 v60, v212, v213
	v_pk_mul_f32 v[210:211], v[12:13], v[210:211]
	v_add_f32_e32 v60, v60, v214
	v_mul_f32_e32 v214, v68, v72
	v_pk_mul_f32 v[212:213], v[20:21], v[78:79]
	v_add_f32_e32 v68, v210, v211
	v_lshlrev_b32_e32 v211, 16, v73
	v_lshlrev_b32_e32 v210, 16, v69
	v_add_f32_e32 v68, v68, v212
	v_pk_mov_b32 v[86:87], v[86:87], v[210:211] op_sel:[1,0]
	v_add_f32_e32 v68, v68, v213
	v_pk_mul_f32 v[212:213], v[88:89], v[86:87]
	v_add_f32_e32 v124, v124, v125
	v_add_f32_e32 v124, v124, v212
	v_add_f32_e32 v124, v124, v213
	v_add_f32_e32 v212, v18, v124
	v_mul_f32_e32 v124, 0xbfb8aa3b, v212
	v_exp_f32_e32 v124, v124
	v_add_f32_e32 v60, v60, v215
	v_add_f32_e32 v60, v17, v60
	v_mul_f32_e32 v64, 0xbfb8aa3b, v60
	v_add_f32_e32 v124, 1.0, v124
	v_exp_f32_e32 v64, v64
	v_add_f32_e32 v68, v17, v68
	v_rcp_f32_e32 v213, v124
	v_pk_mul_f32 v[124:125], v[88:89], v[210:211]
	v_add_f32_e32 v134, v134, v135
	v_mul_f32_e32 v72, 0xbfb8aa3b, v68
	v_add_f32_e32 v124, v134, v124
	v_exp_f32_e32 v72, v72
	v_add_f32_e32 v124, v124, v125
	v_mul_f32_e32 v215, v219, v220
	v_add_f32_e32 v219, v18, v124
	v_add_f32_e32 v64, 1.0, v64
	v_mul_f32_e32 v124, 0xbfb8aa3b, v219
	v_rcp_f32_e32 v64, v64
	v_exp_f32_e32 v124, v124
	v_add_f32_e32 v72, 1.0, v72
	v_rcp_f32_e32 v72, v72
	v_pk_mul_f32 v[134:135], v[116:117], v[86:87]
	v_lshlrev_b32_e32 v87, 16, v65
	v_lshlrev_b32_e32 v86, 16, v61
	v_mul_f32_e32 v220, v60, v64
	v_add_f32_e32 v60, 1.0, v124
	v_pk_mov_b32 v[124:125], v[210:211], v[86:87] op_sel:[1,0]
	v_mul_f32_e32 v222, v212, v213
	v_pk_mul_f32 v[212:213], v[116:117], v[210:211]
	v_pk_mul_f32 v[210:211], v[88:89], v[124:125]
	v_add_f32_e32 v64, v134, v135
	v_mul_f32_e32 v221, v68, v72
	v_add_f32_e32 v64, v64, v210
	v_pk_mul_f32 v[134:135], v[88:89], v[86:87]
	v_add_f32_e32 v72, v212, v213
	v_add_f32_e32 v64, v64, v211
	v_add_f32_e32 v72, v72, v134
	v_add_f32_e32 v64, v18, v64
	v_add_f32_e32 v72, v72, v135
	v_mul_f32_e32 v68, 0xbfb8aa3b, v64
	v_add_f32_e32 v134, v18, v72
	v_exp_f32_e32 v68, v68
	v_mul_f32_e32 v72, 0xbfb8aa3b, v134
	v_exp_f32_e32 v72, v72
	v_and_b32_e32 v73, 0xffff0000, v73
	v_add_f32_e32 v68, 1.0, v68
	v_rcp_f32_e32 v135, v68
	v_add_f32_e32 v68, 1.0, v72
	v_and_b32_e32 v72, 0xffff0000, v69
	v_rcp_f32_e32 v210, v68
	v_pk_mov_b32 v[68:69], v[120:121], v[72:73] op_sel:[1,0]
	v_pk_mul_f32 v[130:131], v[14:15], v[120:121]
	v_pk_mul_f32 v[120:121], v[22:23], v[68:69]
	v_add_f32_e32 v132, v132, v133
	v_add_f32_e32 v120, v132, v120
	v_add_f32_e32 v120, v120, v121
	v_add_f32_e32 v132, v19, v120
	v_mul_f32_e32 v120, 0xbfb8aa3b, v132
	v_rcp_f32_e32 v60, v60
	v_exp_f32_e32 v120, v120
	v_mul_f32_e32 v212, v64, v135
	v_and_b32_e32 v65, 0xffff0000, v65
	v_mul_f32_e32 v211, v219, v60
	v_add_f32_e32 v60, 1.0, v120
	v_rcp_f32_e32 v133, v60
	v_pk_mul_f32 v[120:121], v[22:23], v[72:73]
	v_add_f32_e32 v60, v130, v131
	v_add_f32_e32 v60, v60, v120
	v_add_f32_e32 v60, v60, v121
	v_add_f32_e32 v130, v19, v60
	v_and_b32_e32 v64, 0xffff0000, v61
	v_mul_f32_e32 v60, 0xbfb8aa3b, v130
	v_pk_mul_f32 v[68:69], v[14:15], v[68:69]
	v_pk_mov_b32 v[120:121], v[72:73], v[64:65] op_sel:[1,0]
	v_exp_f32_e32 v131, v60
	v_pk_mul_f32 v[60:61], v[22:23], v[120:121]
	v_add_f32_e32 v68, v68, v69
	v_add_f32_e32 v60, v68, v60
	v_add_f32_e32 v60, v60, v61
	v_mul_f32_e32 v210, v134, v210
	v_add_f32_e32 v134, v19, v60
	v_mul_f32_e32 v60, 0xbfb8aa3b, v134
	v_exp_f32_e32 v68, v60
	v_add_f32_e32 v60, 1.0, v131
	v_rcp_f32_e32 v131, v60
	v_pk_mul_f32 v[60:61], v[14:15], v[72:73]
	v_add_f32_e32 v68, 1.0, v68
	v_rcp_f32_e32 v72, v68
	v_pk_mul_f32 v[68:69], v[22:23], v[64:65]
	v_add_f32_e32 v60, v60, v61
	v_add_f32_e32 v60, v60, v68
	v_add_f32_e32 v60, v60, v69
	v_add_f32_e32 v135, v19, v60
	v_mul_f32_e32 v60, 0xbfb8aa3b, v135
	v_exp_f32_e32 v60, v60
	v_lshlrev_b32_e32 v69, 16, v74
	v_lshlrev_b32_e32 v68, 16, v70
	v_mul_f32_e32 v219, v130, v131
	v_add_f32_e32 v60, 1.0, v60
	v_rcp_f32_e32 v130, v60
	v_pk_mov_b32 v[60:61], v[112:113], v[68:69] op_sel:[1,0]
	v_mul_f32_e32 v209, v126, v127
	v_pk_mul_f32 v[126:127], v[104:105], v[112:113]
	v_mul_f32_e32 v223, v134, v72
	v_pk_mul_f32 v[72:73], v[90:91], v[60:61]
	v_add_f32_e32 v112, v128, v129
	v_add_f32_e32 v72, v112, v72
	v_add_f32_e32 v72, v72, v73
	v_add_f32_e32 v128, v4, v72
	v_mul_f32_e32 v72, 0xbfb8aa3b, v128
	v_exp_f32_e32 v112, v72
	v_pk_mul_f32 v[72:73], v[90:91], v[68:69]
	v_add_f32_e32 v113, v126, v127
	v_add_f32_e32 v72, v113, v72
	v_add_f32_e32 v72, v72, v73
	v_add_f32_e32 v129, v4, v72
	v_mul_f32_e32 v72, 0xbfb8aa3b, v129
	v_exp_f32_e32 v72, v72
	v_add_f32_e32 v73, 1.0, v112
	v_mul_f32_e32 v224, v135, v130
	v_rcp_f32_e32 v130, v73
	v_add_f32_e32 v72, 1.0, v72
	v_rcp_f32_e32 v131, v72
	v_pk_mul_f32 v[72:73], v[104:105], v[60:61]
	v_lshlrev_b32_e32 v61, 16, v66
	v_lshlrev_b32_e32 v60, 16, v62
	v_pk_mov_b32 v[112:113], v[68:69], v[60:61] op_sel:[1,0]
	v_add_f32_e32 v72, v72, v73
	v_pk_mul_f32 v[126:127], v[90:91], v[112:113]
	v_pk_mul_f32 v[68:69], v[104:105], v[68:69]
	v_add_f32_e32 v72, v72, v126
	v_add_f32_e32 v72, v72, v127
	v_add_f32_e32 v126, v4, v72
	v_mul_f32_e32 v72, 0xbfb8aa3b, v126
	v_exp_f32_e32 v72, v72
	v_add_f32_e32 v68, v68, v69
; #define LAS __attribute__((address_space(3)))
; __device__ __forceinline__ unsigned cvt_pk_bf16(float lo, float hi) { unsigned r; asm volatile("v_cvt_pk_bf16_f32 %0, %1, %2" : "=v"(r) : "v"(lo), "v"(hi)); return r; }
; template <bool WITH_C, bool B_TR>
; __device__ __forceinline__ void ssd_stage(const Params& p, LAS unsigned char* lds, int b, int c, int g) {
;     ...
;         for (int hb = 0; hb < 2; ++hb) {
;             float y[8][8];
; #pragma unroll
;             for (int tt = 0; tt < 8; ++tt) {
;                 float u0[8]; unpack8(rows[3 + 8 * hb + tt], u0);
; #pragma unroll
;                 for (int i = 0; i < 8; ++i) { const float a = w0[i] * u3[i] + w1[i] * u2[i] + w2[i] * u1[i] + w3[i] * u0[i] + bs[i]; y[tt][i] = a * __builtin_amdgcn_rcpf(1.f + __expf(-a)); u3[i] = u2[i]; u2[i] = u1[i]; u1[i] = u0[i]; }
;             }
;             const bool tr = (kind == 0) || (kind == 1 && B_TR);
;             if (tr) {
;                 LAS unsigned char* img = lds + (kind == 0 ? SSD_XT : SSD_B);
;                 const int r0 = kind == 0 ? 8 * cg : 8 * (cg - 64);
; #pragma unroll
;                 for (int i = 0; i < 8; ++i) { u32x4 w; w.x = pg8::cvt_pk_bf16(y[0][i], y[1][i]); w.y = pg8::cvt_pk_bf16(y[2][i], y[3][i]); w.z = pg8::cvt_pk_bf16(y[4][i], y[5][i]); w.w = pg8::cvt_pk_bf16(y[6][i], y[7][i]);
;                     *(LAS u32x4*)(img + ((r0 + i) * 72 + 16 * seg + 8 * hb) * 2) = w; }
	v_mul_f32_e32 v225, v128, v130
	v_mul_f32_e32 v226, v129, v131
	v_add_f32_e32 v127, 1.0, v72
	v_pk_mul_f32 v[72:73], v[90:91], v[60:61]
	v_pk_mul_f32 v[122:123], v[0:1], v[100:101]
	v_add_f32_e32 v68, v68, v72
	v_add_f32_e32 v68, v68, v73
	v_add_f32_e32 v128, v4, v68
	v_mul_f32_e32 v68, 0xbfb8aa3b, v128
	v_and_b32_e32 v73, 0xffff0000, v74
	v_and_b32_e32 v72, 0xffff0000, v70
	v_exp_f32_e32 v129, v68
	v_pk_mov_b32 v[68:69], v[100:101], v[72:73] op_sel:[1,0]
	v_add_f32_e32 v70, v114, v115
	v_pk_mul_f32 v[100:101], v[8:9], v[68:69]
	v_add_co_u32_e32 v26, vcc, s4, v24
	v_add_f32_e32 v70, v70, v100
	v_add_f32_e32 v70, v70, v101
	v_add_f32_e32 v70, v5, v70
	v_mul_f32_e32 v74, 0xbfb8aa3b, v70
	v_add_f32_e32 v100, 1.0, v129
	v_exp_f32_e32 v74, v74
	v_rcp_f32_e32 v115, v100
	v_pk_mul_f32 v[100:101], v[8:9], v[72:73]
	v_add_f32_e32 v122, v122, v123
	v_addc_co_u32_e32 v27, vcc, 0, v25, vcc
	s_mov_b32 s4, 0xd000
	v_add_f32_e32 v100, v122, v100
	v_add_co_u32_e32 v28, vcc, s4, v24
	v_add_f32_e32 v100, v100, v101
	s_nop 0
	v_addc_co_u32_e32 v29, vcc, 0, v25, vcc
	s_nop 0
	s_nop 0
	v_rcp_f32_e32 v114, v127
	v_add_f32_e32 v127, v5, v100
	v_add_f32_e32 v74, 1.0, v74
	v_mul_f32_e32 v100, 0xbfb8aa3b, v127
	v_rcp_f32_e32 v74, v74
	v_exp_f32_e32 v100, v100
	v_mul_f32_e32 v227, v126, v114
	v_mul_f32_e32 v228, v128, v115
	v_mul_f32_e32 v229, v70, v74
	v_add_f32_e32 v70, 1.0, v100
	v_pk_mul_f32 v[100:101], v[0:1], v[68:69]
	v_and_b32_e32 v69, 0xffff0000, v66
	v_and_b32_e32 v68, 0xffff0000, v62
	v_pk_mov_b32 v[122:123], v[72:73], v[68:69] op_sel:[1,0]
	v_pk_mul_f32 v[114:115], v[0:1], v[72:73]
	v_pk_mul_f32 v[72:73], v[8:9], v[122:123]
	v_add_f32_e32 v62, v100, v101
	v_add_f32_e32 v62, v62, v72
	v_add_f32_e32 v62, v62, v73
	v_pk_mul_f32 v[72:73], v[8:9], v[68:69]
	v_add_f32_e32 v74, v114, v115
	v_add_f32_e32 v72, v74, v72
	v_add_f32_e32 v72, v72, v73
	v_add_f32_e32 v74, v5, v72
	v_mul_f32_e32 v72, 0xbfb8aa3b, v74
	v_exp_f32_e32 v72, v72
	v_add_f32_e32 v62, v5, v62
	v_lshlrev_b32_e32 v101, 16, v75
	v_lshlrev_b32_e32 v100, 16, v71
	v_add_f32_e32 v72, 1.0, v72
	v_mul_f32_e32 v66, 0xbfb8aa3b, v62
	v_rcp_f32_e32 v114, v72
	v_pk_mov_b32 v[72:73], v[92:93], v[100:101] op_sel:[1,0]
	v_pk_mul_f32 v[108:109], v[96:97], v[92:93]
	v_exp_f32_e32 v66, v66
	v_pk_mul_f32 v[92:93], v[84:85], v[72:73]
	v_add_f32_e32 v110, v110, v111
	v_add_f32_e32 v92, v110, v92
	v_add_f32_e32 v92, v92, v93
	v_add_f32_e32 v115, v6, v92
	v_add_f32_e32 v66, 1.0, v66
	v_mul_f32_e32 v92, 0xbfb8aa3b, v115
	v_rcp_f32_e32 v66, v66
	v_exp_f32_e32 v92, v92
	v_mul_f32_e32 v232, v74, v114
	v_rcp_f32_e32 v70, v70
	v_mul_f32_e32 v231, v62, v66
	v_add_f32_e32 v62, 1.0, v92
	v_pk_mul_f32 v[92:93], v[84:85], v[100:101]
	v_add_f32_e32 v66, v108, v109
	v_add_f32_e32 v66, v66, v92
	v_add_f32_e32 v66, v66, v93
	v_pk_mul_f32 v[92:93], v[96:97], v[72:73]
	v_lshlrev_b32_e32 v73, 16, v67
	v_lshlrev_b32_e32 v72, 16, v63
	v_pk_mov_b32 v[108:109], v[100:101], v[72:73] op_sel:[1,0]
	v_add_f32_e32 v74, v92, v93
	v_pk_mul_f32 v[110:111], v[84:85], v[108:109]
	v_add_f32_e32 v66, v6, v66
	v_add_f32_e32 v74, v74, v110
	v_add_f32_e32 v74, v74, v111
	v_add_f32_e32 v74, v6, v74
	v_mul_f32_e32 v92, 0xbfb8aa3b, v74
	v_mul_f32_e32 v230, v127, v70
	v_mul_f32_e32 v70, 0xbfb8aa3b, v66
	v_exp_f32_e32 v110, v92
	v_exp_f32_e32 v70, v70
	v_pk_mul_f32 v[92:93], v[96:97], v[100:101]
	v_and_b32_e32 v75, 0xffff0000, v75
	v_add_f32_e32 v100, 1.0, v110
	v_add_f32_e32 v70, 1.0, v70
	v_rcp_f32_e32 v110, v100
	v_pk_mul_f32 v[100:101], v[84:85], v[72:73]
	v_add_f32_e32 v92, v92, v93
	v_rcp_f32_e32 v70, v70
	v_add_f32_e32 v92, v92, v100
	v_add_f32_e32 v92, v92, v101
	v_add_f32_e32 v92, v6, v92
	v_mul_f32_e32 v93, 0xbfb8aa3b, v92
	v_mul_f32_e32 v235, v74, v110
	v_and_b32_e32 v74, 0xffff0000, v71
	v_rcp_f32_e32 v62, v62
	v_exp_f32_e32 v93, v93
	v_mul_f32_e32 v234, v66, v70
	v_pk_mov_b32 v[70:71], v[80:81], v[74:75] op_sel:[1,0]
	v_pk_mul_f32 v[94:95], v[2:3], v[80:81]
	v_pk_mul_f32 v[80:81], v[10:11], v[70:71]
	v_add_f32_e32 v66, v98, v99
	v_add_f32_e32 v66, v66, v80
	v_add_f32_e32 v66, v66, v81
	v_pk_mul_f32 v[80:81], v[10:11], v[74:75]
	v_add_f32_e32 v94, v94, v95
	v_mul_f32_e32 v233, v115, v62
	v_add_f32_e32 v62, 1.0, v93
	v_add_f32_e32 v93, v7, v66
	v_add_f32_e32 v80, v94, v80
	v_mul_f32_e32 v66, 0xbfb8aa3b, v93
	v_add_f32_e32 v80, v80, v81
	v_rcp_f32_e32 v62, v62
	v_exp_f32_e32 v66, v66
	v_add_f32_e32 v94, v7, v80
	v_mul_f32_e32 v80, 0xbfb8aa3b, v94
	v_exp_f32_e32 v80, v80
	v_mul_f32_e32 v236, v92, v62
	v_add_f32_e32 v62, 1.0, v66
	v_and_b32_e32 v67, 0xffff0000, v67
	v_and_b32_e32 v66, 0xffff0000, v63
	v_rcp_f32_e32 v92, v62
	v_pk_mul_f32 v[70:71], v[2:3], v[70:71]
	v_pk_mov_b32 v[62:63], v[74:75], v[66:67] op_sel:[1,0]
	v_add_f32_e32 v95, 1.0, v80
	v_pk_mul_f32 v[80:81], v[2:3], v[74:75]
	v_pk_mul_f32 v[74:75], v[10:11], v[62:63]
	v_add_f32_e32 v70, v70, v71
	v_add_f32_e32 v70, v70, v74
	v_add_f32_e32 v70, v70, v75
	v_add_f32_e32 v74, v7, v70
	v_mul_f32_e32 v70, 0xbfb8aa3b, v74
	v_exp_f32_e32 v75, v70
	v_pk_mul_f32 v[70:71], v[10:11], v[66:67]
	v_add_f32_e32 v80, v80, v81
	v_add_f32_e32 v70, v80, v70
	v_add_f32_e32 v70, v70, v71
	v_add_f32_e32 v70, v7, v70
	v_mul_f32_e32 v71, 0xbfb8aa3b, v70
	v_exp_f32_e32 v71, v71
	v_add_f32_e32 v75, 1.0, v75
	v_rcp_f32_e32 v75, v75
	v_rcp_f32_e32 v80, v95
	v_add_f32_e32 v71, 1.0, v71
	v_rcp_f32_e32 v71, v71
	s_movk_i32 s2, 0x48
	v_mul_f32_e32 v239, v74, v75
	v_pk_mul_f32 v[74:75], v[2:3], v[62:63]
	v_mul_lo_u32 v62, v186, s2
	v_or_b32_e32 v63, v62, v138
	v_add_u32_e32 v62, v138, v62
	v_lshl_add_u32 v115, v63, 1, v185
	v_lshl_add_u32 v114, v62, 1, v185
	s_waitcnt vmcnt(4)
; #define LAS __attribute__((address_space(3)))
; __device__ __forceinline__ unsigned cvt_pk_bf16(float lo, float hi) { unsigned r; asm volatile("v_cvt_pk_bf16_f32 %0, %1, %2" : "=v"(r) : "v"(lo), "v"(hi)); return r; }
; template <bool WITH_C, bool B_TR>
; __device__ __forceinline__ void ssd_stage(const Params& p, LAS unsigned char* lds, int b, int c, int g) {
;     ...
;         for (int hb = 0; hb < 2; ++hb) {
;             float y[8][8];
; #pragma unroll
;             for (int tt = 0; tt < 8; ++tt) {
;                 float u0[8]; unpack8(rows[3 + 8 * hb + tt], u0);
; #pragma unroll
;                 for (int i = 0; i < 8; ++i) { const float a = w0[i] * u3[i] + w1[i] * u2[i] + w2[i] * u1[i] + w3[i] * u0[i] + bs[i]; y[tt][i] = a * __builtin_amdgcn_rcpf(1.f + __expf(-a)); u3[i] = u2[i]; u2[i] = u1[i]; u1[i] = u0[i]; }
;             }
;             const bool tr = (kind == 0) || (kind == 1 && B_TR);
;             if (tr) {
;                 LAS unsigned char* img = lds + (kind == 0 ? SSD_XT : SSD_B);
;                 const int r0 = kind == 0 ? 8 * cg : 8 * (cg - 64);
; #pragma unroll
;                 for (int i = 0; i < 8; ++i) { u32x4 w; w.x = pg8::cvt_pk_bf16(y[0][i], y[1][i]); w.y = pg8::cvt_pk_bf16(y[2][i], y[3][i]); w.z = pg8::cvt_pk_bf16(y[4][i], y[5][i]); w.w = pg8::cvt_pk_bf16(y[6][i], y[7][i]);
;                     *(LAS u32x4*)(img + ((r0 + i) * 72 + 16 * seg + 8 * hb) * 2) = w; }
	v_lshlrev_b32_e32 v63, 16, v56
	v_lshlrev_b32_e32 v62, 16, v52
	v_mul_f32_e32 v238, v94, v80
	v_mul_f32_e32 v240, v70, v71
	v_pk_mul_f32 v[70:71], v[118:119], v[82:83]
	v_pk_mul_f32 v[94:95], v[118:119], v[76:77]
	v_pk_mov_b32 v[76:77], v[76:77], v[62:63] op_sel:[1,0]
	v_add_f32_e32 v70, v70, v71
	v_pk_mul_f32 v[80:81], v[106:107], v[76:77]
	s_mov_b32 s4, 0xf000
	v_add_f32_e32 v70, v70, v80
	v_add_f32_e32 v70, v70, v81
	v_add_co_u32_e32 v26, vcc, s4, v24
	v_add_f32_e32 v70, v16, v70
	s_nop 0
	v_addc_co_u32_e32 v27, vcc, 0, v25, vcc
	s_mov_b32 s4, 0x10000
	v_mul_f32_e32 v71, 0xbfb8aa3b, v70
	v_add_co_u32_e32 v28, vcc, s4, v24
	v_exp_f32_e32 v71, v71
	s_nop 0
	v_addc_co_u32_e32 v29, vcc, 0, v25, vcc
	s_mov_b32 s4, 0x12000
	s_nop 0
	s_nop 0
	v_add_co_u32_e32 v26, vcc, s4, v24
	s_mov_b32 s4, 0x13000
	s_nop 0
	v_addc_co_u32_e32 v27, vcc, 0, v25, vcc
	v_add_co_u32_e32 v28, vcc, s4, v24
	v_add_f32_e32 v71, 1.0, v71
	s_nop 0
	v_addc_co_u32_e32 v29, vcc, 0, v25, vcc
	s_mov_b32 s4, 0x15000
	v_rcp_f32_e32 v71, v71
	s_nop 0
	s_nop 0
	global_load_dwordx4 v[28:31], v[28:29], off offset:2048
	v_add_co_u32_e32 v26, vcc, s4, v24
	s_mov_b32 s4, 0x16000
	s_nop 0
	v_addc_co_u32_e32 v27, vcc, 0, v25, vcc
	v_add_co_u32_e32 v24, vcc, s4, v24
	v_mul_f32_e32 v70, v70, v71
	s_nop 0
	v_addc_co_u32_e32 v25, vcc, 0, v25, vcc
	global_load_dwordx4 v[32:35], v[26:27], off
	s_nop 0
	global_load_dwordx4 v[24:27], v[24:25], off offset:2048
	v_cvt_pk_bf16_f32 v98, v191, v208
	v_cvt_pk_bf16_f32 v99, v209, v195
	v_cvt_pk_bf16_f32 v100, v218, v216
	v_cvt_pk_bf16_f32 v101, v217, v70
	v_pk_mul_f32 v[70:71], v[106:107], v[62:63]
	v_add_f32_e32 v94, v94, v95
	v_add_f32_e32 v70, v94, v70
	v_add_f32_e32 v70, v70, v71
	ds_write_b128 v115, v[98:101]
	v_add_f32_e32 v98, v16, v70
	v_mul_f32_e32 v70, 0xbfb8aa3b, v98
	v_exp_f32_e32 v70, v70
	v_and_b32_e32 v71, 0xffff0000, v56
	v_pk_mul_f32 v[82:83], v[12:13], v[102:103]
	v_pk_mul_f32 v[126:127], v[14:15], v[120:121]
	v_add_f32_e32 v70, 1.0, v70
	v_rcp_f32_e32 v99, v70
	v_and_b32_e32 v70, 0xffff0000, v52
	v_pk_mul_f32 v[120:121], v[12:13], v[78:79]
	v_pk_mov_b32 v[78:79], v[78:79], v[70:71] op_sel:[1,0]
	v_add_f32_e32 v52, v82, v83
	v_pk_mul_f32 v[94:95], v[20:21], v[78:79]
	v_pk_mul_f32 v[82:83], v[20:21], v[70:71]
	v_add_f32_e32 v52, v52, v94
	v_add_f32_e32 v94, v120, v121
	v_add_f32_e32 v82, v94, v82
	v_add_f32_e32 v52, v52, v95
	v_add_f32_e32 v82, v82, v83
	v_add_f32_e32 v52, v17, v52
	v_add_f32_e32 v82, v17, v82
	v_mul_f32_e32 v56, 0xbfb8aa3b, v52
	v_mul_f32_e32 v83, 0xbfb8aa3b, v82
	v_exp_f32_e32 v56, v56
	v_exp_f32_e32 v83, v83
	v_pk_mul_f32 v[100:101], v[118:119], v[76:77]
	v_lshlrev_b32_e32 v77, 16, v57
	v_add_f32_e32 v56, 1.0, v56
	v_add_f32_e32 v83, 1.0, v83
	v_rcp_f32_e32 v56, v56
	v_rcp_f32_e32 v83, v83
	v_lshlrev_b32_e32 v76, 16, v53
	v_pk_mul_f32 v[102:103], v[116:117], v[124:125]
	v_mul_f32_e32 v52, v52, v56
	v_mul_f32_e32 v120, v82, v83
	v_pk_mov_b32 v[82:83], v[86:87], v[76:77] op_sel:[1,0]
	v_mul_f32_e32 v237, v93, v92
	v_pk_mul_f32 v[130:131], v[0:1], v[122:123]
	v_pk_mul_f32 v[92:93], v[96:97], v[108:109]
	v_pk_mul_f32 v[122:123], v[116:117], v[86:87]
	v_cvt_pk_bf16_f32 v108, v190, v206
	v_cvt_pk_bf16_f32 v109, v207, v214
	v_cvt_pk_bf16_f32 v110, v215, v220
	v_cvt_pk_bf16_f32 v111, v221, v52
	v_pk_mul_f32 v[86:87], v[88:89], v[82:83]
	v_add_f32_e32 v52, v102, v103
	v_add_f32_e32 v52, v52, v86
	v_mul_f32_e32 v121, v98, v99
	v_add_f32_e32 v52, v52, v87
	v_pk_mul_f32 v[86:87], v[88:89], v[76:77]
	v_add_f32_e32 v98, v122, v123
	v_add_f32_e32 v52, v18, v52
	v_add_f32_e32 v86, v98, v86
	v_mul_f32_e32 v56, 0xbfb8aa3b, v52
	v_add_f32_e32 v86, v86, v87
	v_exp_f32_e32 v56, v56
	v_add_f32_e32 v86, v18, v86
	v_mul_f32_e32 v87, 0xbfb8aa3b, v86
	v_exp_f32_e32 v87, v87
	v_add_f32_e32 v56, 1.0, v56
	v_rcp_f32_e32 v56, v56
	v_and_b32_e32 v57, 0xffff0000, v57
	v_add_f32_e32 v87, 1.0, v87
	v_rcp_f32_e32 v87, v87
	v_mul_f32_e32 v52, v52, v56
	v_and_b32_e32 v56, 0xffff0000, v53
	ds_write_b128 v114, v[108:111] offset:144
	v_cvt_pk_bf16_f32 v108, v189, v204
	v_cvt_pk_bf16_f32 v109, v199, v222
	v_cvt_pk_bf16_f32 v110, v211, v212
	v_cvt_pk_bf16_f32 v111, v210, v52
	v_pk_mov_b32 v[52:53], v[64:65], v[56:57] op_sel:[1,0]
	v_mul_f32_e32 v213, v132, v133
	v_pk_mul_f32 v[132:133], v[14:15], v[64:65]
	v_mul_f32_e32 v122, v86, v87
	v_pk_mul_f32 v[64:65], v[22:23], v[52:53]
	v_add_f32_e32 v86, v126, v127
	v_add_f32_e32 v64, v86, v64
	v_add_f32_e32 v64, v64, v65
	v_add_f32_e32 v86, v19, v64
	v_mul_f32_e32 v64, 0xbfb8aa3b, v86
	v_exp_f32_e32 v87, v64
	v_pk_mul_f32 v[64:65], v[22:23], v[56:57]
	v_add_f32_e32 v98, v132, v133
	v_add_f32_e32 v64, v98, v64
	v_add_f32_e32 v64, v64, v65
	v_add_f32_e32 v64, v19, v64
	v_mul_f32_e32 v65, 0xbfb8aa3b, v64
	v_exp_f32_e32 v65, v65
	v_add_f32_e32 v87, 1.0, v87
	v_rcp_f32_e32 v87, v87
	v_pk_mul_f32 v[128:129], v[104:105], v[112:113]
	v_add_f32_e32 v65, 1.0, v65
	v_rcp_f32_e32 v65, v65
	v_mul_f32_e32 v98, v86, v87
	v_pk_mul_f32 v[86:87], v[14:15], v[52:53]
	v_lshlrev_b32_e32 v53, 16, v58
	v_lshlrev_b32_e32 v52, 16, v54
	v_pk_mul_f32 v[134:135], v[104:105], v[60:61]
	v_pk_mov_b32 v[60:61], v[60:61], v[52:53] op_sel:[1,0]
	ds_write_b128 v114, v[108:111] offset:288
	v_cvt_pk_bf16_f32 v124, v188, v205
	v_cvt_pk_bf16_f32 v125, v203, v213
	v_cvt_pk_bf16_f32 v126, v219, v223
	v_mul_f32_e32 v123, v64, v65
	v_cvt_pk_bf16_f32 v127, v224, v98
	v_pk_mul_f32 v[64:65], v[90:91], v[60:61]
	v_add_f32_e32 v98, v128, v129
	v_add_f32_e32 v64, v98, v64
	v_add_f32_e32 v64, v64, v65
	v_add_f32_e32 v98, v4, v64
	v_mul_f32_e32 v64, 0xbfb8aa3b, v98
	v_exp_f32_e32 v99, v64
	v_pk_mul_f32 v[64:65], v[90:91], v[52:53]
	v_add_f32_e32 v110, v134, v135
; #define LAS __attribute__((address_space(3)))
; __device__ __forceinline__ unsigned cvt_pk_bf16(float lo, float hi) { unsigned r; asm volatile("v_cvt_pk_bf16_f32 %0, %1, %2" : "=v"(r) : "v"(lo), "v"(hi)); return r; }
; template <bool WITH_C, bool B_TR>
; __device__ __forceinline__ void ssd_stage(const Params& p, LAS unsigned char* lds, int b, int c, int g) {
;     ...
;         for (int hb = 0; hb < 2; ++hb) {
;             float y[8][8];
; #pragma unroll
;             for (int tt = 0; tt < 8; ++tt) {
;                 float u0[8]; unpack8(rows[3 + 8 * hb + tt], u0);
; #pragma unroll
;                 for (int i = 0; i < 8; ++i) { const float a = w0[i] * u3[i] + w1[i] * u2[i] + w2[i] * u1[i] + w3[i] * u0[i] + bs[i]; y[tt][i] = a * __builtin_amdgcn_rcpf(1.f + __expf(-a)); u3[i] = u2[i]; u2[i] = u1[i]; u1[i] = u0[i]; }
;             }
;             const bool tr = (kind == 0) || (kind == 1 && B_TR);
;             if (tr) {
;                 LAS unsigned char* img = lds + (kind == 0 ? SSD_XT : SSD_B);
;                 const int r0 = kind == 0 ? 8 * cg : 8 * (cg - 64);
; #pragma unroll
;                 for (int i = 0; i < 8; ++i) { u32x4 w; w.x = pg8::cvt_pk_bf16(y[0][i], y[1][i]); w.y = pg8::cvt_pk_bf16(y[2][i], y[3][i]); w.z = pg8::cvt_pk_bf16(y[4][i], y[5][i]); w.w = pg8::cvt_pk_bf16(y[6][i], y[7][i]);
;                     *(LAS u32x4*)(img + ((r0 + i) * 72 + 16 * seg + 8 * hb) * 2) = w; }
	v_add_f32_e32 v64, v110, v64
	v_add_f32_e32 v64, v64, v65
	v_add_f32_e32 v64, v4, v64
	v_mul_f32_e32 v65, 0xbfb8aa3b, v64
	v_exp_f32_e32 v65, v65
	v_add_f32_e32 v99, 1.0, v99
	v_rcp_f32_e32 v99, v99
	ds_write_b128 v114, v[124:127] offset:432
	v_add_f32_e32 v65, 1.0, v65
	v_rcp_f32_e32 v65, v65
	v_pk_mul_f32 v[208:209], v[0:1], v[68:69]
	v_mul_f32_e32 v98, v98, v99
	v_cvt_pk_bf16_f32 v126, v187, v201
	v_mul_f32_e32 v124, v64, v65
	v_and_b32_e32 v65, 0xffff0000, v58
	v_and_b32_e32 v64, 0xffff0000, v54
	v_pk_mov_b32 v[68:69], v[68:69], v[64:65] op_sel:[1,0]
	v_cvt_pk_bf16_f32 v127, v202, v225
	v_cvt_pk_bf16_f32 v128, v226, v227
	v_cvt_pk_bf16_f32 v129, v228, v98
	v_add_f32_e32 v54, v130, v131
	v_pk_mul_f32 v[98:99], v[8:9], v[68:69]
	v_add_f32_e32 v110, v208, v209
	v_add_f32_e32 v54, v54, v98
	v_add_f32_e32 v54, v54, v99
	v_pk_mul_f32 v[98:99], v[8:9], v[64:65]
	v_add_f32_e32 v54, v5, v54
	v_add_f32_e32 v98, v110, v98
	v_add_f32_e32 v98, v98, v99
	v_add_f32_e32 v98, v5, v98
	v_mul_f32_e32 v99, 0xbfb8aa3b, v98
	v_mul_f32_e32 v58, 0xbfb8aa3b, v54
	v_exp_f32_e32 v99, v99
	v_exp_f32_e32 v58, v58
	v_pk_mul_f32 v[110:111], v[0:1], v[68:69]
	v_pk_mul_f32 v[112:113], v[96:97], v[72:73]
	v_add_f32_e32 v99, 1.0, v99
	v_add_f32_e32 v58, 1.0, v58
	v_rcp_f32_e32 v99, v99
	v_rcp_f32_e32 v58, v58
	ds_write_b128 v114, v[126:129] offset:576
	v_cvt_pk_bf16_f32 v126, v184, v198
	v_mul_f32_e32 v125, v98, v99
	v_lshlrev_b32_e32 v99, 16, v59
	v_lshlrev_b32_e32 v98, 16, v55
	v_mul_f32_e32 v54, v54, v58
	v_pk_mov_b32 v[68:69], v[72:73], v[98:99] op_sel:[1,0]
	v_cvt_pk_bf16_f32 v127, v193, v229
	v_cvt_pk_bf16_f32 v128, v230, v231
	v_cvt_pk_bf16_f32 v129, v232, v54
	v_add_f32_e32 v54, v92, v93
	v_pk_mul_f32 v[72:73], v[84:85], v[68:69]
	v_add_f32_e32 v92, v112, v113
	v_add_f32_e32 v54, v54, v72
	v_add_f32_e32 v54, v54, v73
	v_add_f32_e32 v54, v6, v54
	v_mul_f32_e32 v58, 0xbfb8aa3b, v54
	v_exp_f32_e32 v58, v58
	v_pk_mul_f32 v[72:73], v[84:85], v[98:99]
	v_and_b32_e32 v59, 0xffff0000, v59
	v_add_f32_e32 v72, v92, v72
	v_add_f32_e32 v72, v72, v73
	v_add_f32_e32 v58, 1.0, v58
	v_add_f32_e32 v72, v6, v72
	v_rcp_f32_e32 v58, v58
	v_mul_f32_e32 v73, 0xbfb8aa3b, v72
	v_exp_f32_e32 v73, v73
	ds_write_b128 v114, v[126:129] offset:720
	v_mul_f32_e32 v54, v54, v58
	v_and_b32_e32 v58, 0xffff0000, v55
	v_cvt_pk_bf16_f32 v126, v183, v200
	v_cvt_pk_bf16_f32 v127, v197, v233
	v_cvt_pk_bf16_f32 v128, v234, v235
	v_cvt_pk_bf16_f32 v129, v236, v54
	v_pk_mov_b32 v[54:55], v[66:67], v[58:59] op_sel:[1,0]
	v_pk_mul_f32 v[80:81], v[2:3], v[66:67]
	v_add_f32_e32 v73, 1.0, v73
	v_pk_mul_f32 v[184:185], v[96:97], v[68:69]
	v_pk_mul_f32 v[66:67], v[10:11], v[54:55]
	v_add_f32_e32 v68, v74, v75
	v_rcp_f32_e32 v73, v73
	v_add_f32_e32 v66, v68, v66
	v_add_f32_e32 v66, v66, v67
	v_add_f32_e32 v68, v7, v66
	v_mul_f32_e32 v66, 0xbfb8aa3b, v68
	v_mul_f32_e32 v112, v72, v73
	v_exp_f32_e32 v69, v66
	v_pk_mul_f32 v[66:67], v[10:11], v[58:59]
	v_add_f32_e32 v73, v80, v81
	v_add_f32_e32 v66, v73, v66
	v_add_f32_e32 v66, v66, v67
	v_add_f32_e32 v66, v7, v66
	v_mul_f32_e32 v67, 0xbfb8aa3b, v66
	v_exp_f32_e32 v67, v67
	s_waitcnt vmcnt(5)
	v_lshlrev_b32_e32 v93, 16, v48
	v_lshlrev_b32_e32 v92, 16, v44
	v_pk_mul_f32 v[94:95], v[118:119], v[62:63]
	v_add_f32_e32 v67, 1.0, v67
	v_rcp_f32_e32 v67, v67
	v_pk_mov_b32 v[62:63], v[62:63], v[92:93] op_sel:[1,0]
	v_pk_mul_f32 v[186:187], v[2:3], v[54:55]
	v_pk_mul_f32 v[54:55], v[106:107], v[62:63]
	v_mul_f32_e32 v113, v66, v67
	v_add_f32_e32 v66, v100, v101
	v_add_f32_e32 v54, v66, v54
	v_add_f32_e32 v54, v54, v55
	v_add_f32_e32 v80, v16, v54
	v_mul_f32_e32 v54, 0xbfb8aa3b, v80
	v_exp_f32_e32 v66, v54
	v_pk_mul_f32 v[54:55], v[106:107], v[92:93]
	v_add_f32_e32 v67, v94, v95
	v_add_f32_e32 v54, v67, v54
	v_add_f32_e32 v54, v54, v55
	v_add_f32_e32 v81, v16, v54
	v_mul_f32_e32 v54, 0xbfb8aa3b, v81
	v_add_f32_e32 v69, 1.0, v69
	v_exp_f32_e32 v54, v54
	v_rcp_f32_e32 v69, v69
	ds_write_b128 v114, v[126:129] offset:864
	v_cvt_pk_bf16_f32 v72, v139, v196
	v_cvt_pk_bf16_f32 v73, v192, v237
	v_add_f32_e32 v55, 1.0, v66
	v_add_f32_e32 v54, 1.0, v54
	v_cvt_pk_bf16_f32 v74, v238, v239
	v_mul_f32_e32 v68, v68, v69
	v_cvt_pk_bf16_f32 v75, v240, v68
	ds_write_b128 v114, v[72:75] offset:1008
	v_rcp_f32_e32 v72, v55
	v_rcp_f32_e32 v73, v54
	v_and_b32_e32 v55, 0xffff0000, v48
	v_and_b32_e32 v54, 0xffff0000, v44
	v_pk_mul_f32 v[78:79], v[12:13], v[78:79]
	v_pk_mov_b32 v[66:67], v[70:71], v[54:55] op_sel:[1,0]
	v_add_f32_e32 v44, v78, v79
	v_pk_mul_f32 v[68:69], v[20:21], v[66:67]
	v_pk_mul_f32 v[102:103], v[12:13], v[70:71]
	v_add_f32_e32 v44, v44, v68
	v_add_f32_e32 v44, v44, v69
	v_add_f32_e32 v44, v17, v44
	v_mul_f32_e32 v48, 0xbfb8aa3b, v44
	v_exp_f32_e32 v48, v48
	v_pk_mul_f32 v[68:69], v[20:21], v[54:55]
	v_add_f32_e32 v70, v102, v103
	v_add_f32_e32 v68, v70, v68
	v_add_f32_e32 v68, v68, v69
	v_mul_f32_e32 v100, v80, v72
	v_add_f32_e32 v72, v17, v68
	v_add_f32_e32 v48, 1.0, v48
	v_mul_f32_e32 v68, 0xbfb8aa3b, v72
	v_rcp_f32_e32 v48, v48
	v_exp_f32_e32 v68, v68
	v_lshlrev_b32_e32 v69, 16, v49
	v_pk_mul_f32 v[82:83], v[116:117], v[82:83]
	v_mul_f32_e32 v102, v44, v48
	v_add_f32_e32 v44, 1.0, v68
	v_lshlrev_b32_e32 v68, 16, v45
	v_pk_mul_f32 v[190:191], v[118:119], v[62:63]
	v_pk_mov_b32 v[62:63], v[76:77], v[68:69] op_sel:[1,0]
	v_add_f32_e32 v48, v82, v83
	v_pk_mul_f32 v[70:71], v[88:89], v[62:63]
	v_mul_f32_e32 v101, v81, v73
	v_add_f32_e32 v48, v48, v70
	v_add_f32_e32 v48, v48, v71
	v_add_f32_e32 v48, v18, v48
	v_mul_f32_e32 v70, 0xbfb8aa3b, v48
	v_rcp_f32_e32 v44, v44
	v_exp_f32_e32 v73, v70
	v_pk_mul_f32 v[108:109], v[116:117], v[76:77]
	v_pk_mul_f32 v[70:71], v[88:89], v[68:69]
; template <bool WITH_C, bool B_TR>
; __device__ __forceinline__ void ssd_stage(const Params& p, LAS unsigned char* lds, int b, int c, int g) {
;     ...
;         for (int hb = 0; hb < 2; ++hb) {
;             float y[8][8];
; #pragma unroll
;             for (int tt = 0; tt < 8; ++tt) {
;                 float u0[8]; unpack8(rows[3 + 8 * hb + tt], u0);
; #pragma unroll
;                 for (int i = 0; i < 8; ++i) { const float a = w0[i] * u3[i] + w1[i] * u2[i] + w2[i] * u1[i] + w3[i] * u0[i] + bs[i]; y[tt][i] = a * __builtin_amdgcn_rcpf(1.f + __expf(-a)); u3[i] = u2[i]; u2[i] = u1[i]; u1[i] = u0[i]; }
	v_add_f32_e32 v74, v108, v109
	v_mul_f32_e32 v109, v72, v44
	v_add_f32_e32 v44, 1.0, v73
	v_rcp_f32_e32 v44, v44
	v_add_f32_e32 v70, v74, v70
	v_and_b32_e32 v75, 0xffff0000, v49
	v_and_b32_e32 v74, 0xffff0000, v45
	v_mul_f32_e32 v103, v48, v44
	v_pk_mov_b32 v[44:45], v[56:57], v[74:75] op_sel:[1,0]
	v_pk_mul_f32 v[132:133], v[14:15], v[56:57]
	v_pk_mul_f32 v[48:49], v[22:23], v[44:45]
	v_add_f32_e32 v56, v86, v87
	v_add_f32_e32 v48, v56, v48
	v_add_f32_e32 v48, v48, v49
	v_add_f32_e32 v70, v70, v71
	v_add_f32_e32 v56, v19, v48
	v_add_f32_e32 v70, v18, v70
	v_mul_f32_e32 v48, 0xbfb8aa3b, v56
	v_mul_f32_e32 v71, 0xbfb8aa3b, v70
	v_pk_mul_f32 v[196:197], v[12:13], v[66:67]
	v_exp_f32_e32 v57, v48
	v_pk_mul_f32 v[48:49], v[22:23], v[74:75]
	v_add_f32_e32 v66, v132, v133
	v_exp_f32_e32 v71, v71
	v_add_f32_e32 v48, v66, v48
	v_add_f32_e32 v48, v48, v49
	v_add_f32_e32 v72, v19, v48
	v_mul_f32_e32 v48, 0xbfb8aa3b, v72
	v_add_f32_e32 v71, 1.0, v71
	v_exp_f32_e32 v48, v48
	v_rcp_f32_e32 v71, v71
	v_add_f32_e32 v49, 1.0, v57
	v_lshlrev_b32_e32 v67, 16, v50
	v_add_f32_e32 v48, 1.0, v48
	v_lshlrev_b32_e32 v66, 16, v46
	v_pk_mul_f32 v[60:61], v[104:105], v[60:61]
	v_mul_f32_e32 v108, v70, v71
	v_pk_mul_f32 v[70:71], v[116:117], v[62:63]
	v_rcp_f32_e32 v57, v49
	v_rcp_f32_e32 v62, v48
	v_pk_mov_b32 v[48:49], v[52:53], v[66:67] op_sel:[1,0]
	v_pk_mul_f32 v[130:131], v[104:105], v[52:53]
	v_pk_mul_f32 v[52:53], v[90:91], v[48:49]
	v_add_f32_e32 v60, v60, v61
	v_add_f32_e32 v52, v60, v52
	v_add_f32_e32 v52, v52, v53
	v_add_f32_e32 v60, v4, v52
	v_mul_f32_e32 v52, 0xbfb8aa3b, v60
	v_exp_f32_e32 v52, v52
	v_mul_f32_e32 v126, v56, v57
	v_add_f32_e32 v57, v130, v131
	v_pk_mul_f32 v[86:87], v[14:15], v[44:45]
	v_add_f32_e32 v52, 1.0, v52
	v_rcp_f32_e32 v56, v52
	v_pk_mul_f32 v[52:53], v[90:91], v[66:67]
	v_and_b32_e32 v61, 0xffff0000, v50
	v_add_f32_e32 v52, v57, v52
	v_add_f32_e32 v52, v52, v53
	v_add_f32_e32 v57, v4, v52
	v_mul_f32_e32 v52, 0xbfb8aa3b, v57
	v_exp_f32_e32 v52, v52
	v_mul_f32_e32 v128, v60, v56
	v_and_b32_e32 v60, 0xffff0000, v46
	v_add_f32_e32 v46, v110, v111
	v_add_f32_e32 v44, 1.0, v52
	v_rcp_f32_e32 v56, v44
	v_pk_mov_b32 v[44:45], v[64:65], v[60:61] op_sel:[1,0]
	v_pk_mul_f32 v[134:135], v[0:1], v[64:65]
	v_pk_mul_f32 v[52:53], v[8:9], v[44:45]
	v_mul_f32_e32 v127, v72, v62
	v_add_f32_e32 v46, v46, v52
	v_add_f32_e32 v46, v46, v53
	v_pk_mul_f32 v[52:53], v[8:9], v[60:61]
	v_add_f32_e32 v62, v134, v135
	v_add_f32_e32 v52, v62, v52
	v_add_f32_e32 v52, v52, v53
	v_add_f32_e32 v52, v5, v52
	v_mul_f32_e32 v53, 0xbfb8aa3b, v52
	v_add_f32_e32 v46, v5, v46
	v_exp_f32_e32 v53, v53
	v_mul_f32_e32 v50, 0xbfb8aa3b, v46
	v_exp_f32_e32 v50, v50
	v_mul_f32_e32 v129, v57, v56
	v_add_f32_e32 v53, 1.0, v53
	v_rcp_f32_e32 v53, v53
	v_add_f32_e32 v50, 1.0, v50
	v_rcp_f32_e32 v50, v50
	v_pk_mul_f32 v[80:81], v[104:105], v[48:49]
	v_mul_f32_e32 v111, v52, v53
	v_lshlrev_b32_e32 v53, 16, v51
	v_lshlrev_b32_e32 v52, 16, v47
	v_pk_mov_b32 v[56:57], v[98:99], v[52:53] op_sel:[1,0]
	v_mul_f32_e32 v110, v46, v50
	v_pk_mul_f32 v[48:49], v[84:85], v[56:57]
	v_add_f32_e32 v46, v184, v185
	v_pk_mul_f32 v[138:139], v[96:97], v[98:99]
	v_add_f32_e32 v46, v46, v48
	v_add_f32_e32 v46, v46, v49
	v_pk_mul_f32 v[48:49], v[84:85], v[52:53]
	v_add_f32_e32 v62, v138, v139
	v_add_f32_e32 v48, v62, v48
	v_add_f32_e32 v50, v6, v46
	v_add_f32_e32 v48, v48, v49
	v_mul_f32_e32 v46, 0xbfb8aa3b, v50
	v_add_f32_e32 v62, v6, v48
	v_exp_f32_e32 v46, v46
	v_mul_f32_e32 v48, 0xbfb8aa3b, v62
	v_exp_f32_e32 v48, v48
	v_pk_mul_f32 v[72:73], v[0:1], v[44:45]
	v_add_f32_e32 v44, 1.0, v46
	v_rcp_f32_e32 v63, v44
	v_add_f32_e32 v44, 1.0, v48
	v_and_b32_e32 v49, 0xffff0000, v51
	v_and_b32_e32 v48, 0xffff0000, v47
	v_rcp_f32_e32 v64, v44
	v_pk_mov_b32 v[44:45], v[58:59], v[48:49] op_sel:[1,0]
	v_add_f32_e32 v51, v186, v187
	v_pk_mul_f32 v[46:47], v[10:11], v[44:45]
	v_pk_mul_f32 v[188:189], v[2:3], v[58:59]
	v_add_f32_e32 v46, v51, v46
	v_add_f32_e32 v46, v46, v47
	v_add_f32_e32 v51, v7, v46
	v_mul_f32_e32 v46, 0xbfb8aa3b, v51
	v_exp_f32_e32 v46, v46
	v_mul_f32_e32 v98, v50, v63
	v_add_f32_e32 v58, v188, v189
	s_waitcnt vmcnt(3)
	v_lshlrev_b32_e32 v59, 16, v40
	v_add_f32_e32 v46, 1.0, v46
	v_rcp_f32_e32 v50, v46
	v_pk_mul_f32 v[46:47], v[10:11], v[48:49]
	v_mul_f32_e32 v99, v62, v64
	v_add_f32_e32 v46, v58, v46
	v_add_f32_e32 v46, v46, v47
	v_add_f32_e32 v131, v7, v46
	v_mul_f32_e32 v46, 0xbfb8aa3b, v131
	v_exp_f32_e32 v46, v46
	v_lshlrev_b32_e32 v58, 16, v36
	v_pk_mul_f32 v[64:65], v[96:97], v[56:57]
	v_mul_f32_e32 v130, v51, v50
	v_add_f32_e32 v46, 1.0, v46
	v_rcp_f32_e32 v56, v46
	v_pk_mov_b32 v[46:47], v[92:93], v[58:59] op_sel:[1,0]
	v_add_f32_e32 v57, v190, v191
	v_pk_mul_f32 v[50:51], v[106:107], v[46:47]
	v_pk_mul_f32 v[192:193], v[118:119], v[92:93]
	v_add_f32_e32 v50, v57, v50
	v_add_f32_e32 v50, v50, v51
	v_add_f32_e32 v93, v16, v50
	v_mul_f32_e32 v50, 0xbfb8aa3b, v93
	v_exp_f32_e32 v132, v50
	v_mul_f32_e32 v92, v131, v56
	v_pk_mul_f32 v[56:57], v[2:3], v[44:45]
	v_pk_mul_f32 v[198:199], v[12:13], v[54:55]
	v_add_f32_e32 v44, 1.0, v132
	v_rcp_f32_e32 v131, v44
	v_pk_mul_f32 v[44:45], v[106:107], v[58:59]
	v_add_f32_e32 v132, v192, v193
	v_add_f32_e32 v44, v132, v44
	v_add_f32_e32 v44, v44, v45
	v_add_f32_e32 v138, v16, v44
	v_mul_f32_e32 v44, 0xbfb8aa3b, v138
	v_exp_f32_e32 v139, v44
	s_waitcnt vmcnt(2)
	v_lshlrev_b32_e32 v44, 16, v28
	s_waitcnt vmcnt(1)
; template <bool WITH_C, bool B_TR>
; __device__ __forceinline__ void ssd_stage(const Params& p, LAS unsigned char* lds, int b, int c, int g) {
;     ...
;         for (int hb = 0; hb < 2; ++hb) {
;             float y[8][8];
; #pragma unroll
;             for (int tt = 0; tt < 8; ++tt) {
;                 float u0[8]; unpack8(rows[3 + 8 * hb + tt], u0);
; #pragma unroll
;                 for (int i = 0; i < 8; ++i) { const float a = w0[i] * u3[i] + w1[i] * u2[i] + w2[i] * u1[i] + w3[i] * u0[i] + bs[i]; y[tt][i] = a * __builtin_amdgcn_rcpf(1.f + __expf(-a)); u3[i] = u2[i]; u2[i] = u1[i]; u1[i] = u0[i]; }
	v_lshlrev_b32_e32 v45, 16, v32
	v_pk_mul_f32 v[132:133], v[118:119], v[46:47]
	v_pk_mov_b32 v[46:47], v[58:59], v[44:45] op_sel:[1,0]
	v_add_f32_e32 v132, v132, v133
	v_pk_mul_f32 v[134:135], v[106:107], v[46:47]
	v_add_f32_e32 v133, 1.0, v139
	v_add_f32_e32 v132, v132, v134
	v_add_f32_e32 v132, v132, v135
	v_add_f32_e32 v134, v16, v132
	v_mul_f32_e32 v132, 0xbfb8aa3b, v134
	v_exp_f32_e32 v132, v132
	v_pk_mul_f32 v[58:59], v[118:119], v[58:59]
	v_rcp_f32_e32 v135, v133
	v_pk_mul_f32 v[94:95], v[116:117], v[68:69]
	v_add_f32_e32 v132, 1.0, v132
	v_rcp_f32_e32 v139, v132
	v_pk_mul_f32 v[132:133], v[106:107], v[44:45]
	v_add_f32_e32 v44, v58, v59
	v_add_f32_e32 v44, v44, v132
	v_add_f32_e32 v44, v44, v133
	v_add_f32_e32 v132, v16, v44
	v_mul_f32_e32 v44, 0xbfb8aa3b, v132
	v_exp_f32_e32 v58, v44
	v_mul_f32_e32 v44, v93, v131
	v_mul_f32_e32 v93, v138, v135
	v_mul_f32_e32 v131, v134, v139
	v_and_b32_e32 v139, 0xffff0000, v40
	v_and_b32_e32 v138, 0xffff0000, v36
	v_add_f32_e32 v58, 1.0, v58
	v_pk_mov_b32 v[54:55], v[54:55], v[138:139] op_sel:[1,0]
	v_rcp_f32_e32 v133, v58
	v_pk_mul_f32 v[58:59], v[20:21], v[54:55]
	v_add_f32_e32 v36, v196, v197
	v_add_f32_e32 v36, v36, v58
	v_add_f32_e32 v36, v36, v59
	v_pk_mul_f32 v[58:59], v[20:21], v[138:139]
	v_add_f32_e32 v134, v198, v199
	v_add_f32_e32 v58, v134, v58
	v_add_f32_e32 v36, v17, v36
	v_add_f32_e32 v58, v58, v59
	v_mul_f32_e32 v40, 0xbfb8aa3b, v36
	v_add_f32_e32 v183, v17, v58
	v_exp_f32_e32 v40, v40
	v_mul_f32_e32 v58, 0xbfb8aa3b, v183
	v_exp_f32_e32 v58, v58
	v_pk_mul_f32 v[134:135], v[12:13], v[54:55]
	v_add_f32_e32 v40, 1.0, v40
	v_rcp_f32_e32 v40, v40
	v_add_f32_e32 v58, 1.0, v58
	v_and_b32_e32 v55, 0xffff0000, v32
	v_and_b32_e32 v54, 0xffff0000, v28
	v_rcp_f32_e32 v186, v58
	v_pk_mov_b32 v[58:59], v[138:139], v[54:55] op_sel:[1,0]
	v_add_f32_e32 v28, v134, v135
	v_pk_mul_f32 v[184:185], v[20:21], v[58:59]
	v_pk_mul_f32 v[138:139], v[12:13], v[138:139]
	v_add_f32_e32 v28, v28, v184
	v_mul_f32_e32 v132, v132, v133
	v_add_f32_e32 v28, v28, v185
	v_mul_f32_e32 v133, v36, v40
	v_pk_mul_f32 v[184:185], v[20:21], v[54:55]
	v_add_f32_e32 v36, v138, v139
	v_lshlrev_b32_e32 v139, 16, v41
	v_lshlrev_b32_e32 v138, 16, v37
	v_add_f32_e32 v36, v36, v184
	v_pk_mov_b32 v[68:69], v[68:69], v[138:139] op_sel:[1,0]
	v_add_f32_e32 v36, v36, v185
	v_pk_mul_f32 v[184:185], v[88:89], v[68:69]
	v_add_f32_e32 v54, v70, v71
	v_add_f32_e32 v54, v54, v184
	v_add_f32_e32 v54, v54, v185
	v_add_f32_e32 v54, v18, v54
	v_mul_f32_e32 v70, 0xbfb8aa3b, v54
	v_exp_f32_e32 v70, v70
	v_add_f32_e32 v28, v17, v28
	v_mul_f32_e32 v32, 0xbfb8aa3b, v28
	v_exp_f32_e32 v32, v32
	v_add_f32_e32 v70, 1.0, v70
	v_add_f32_e32 v36, v17, v36
	v_rcp_f32_e32 v135, v70
	v_pk_mul_f32 v[70:71], v[88:89], v[138:139]
	v_add_f32_e32 v94, v94, v95
	v_mul_f32_e32 v40, 0xbfb8aa3b, v36
	v_add_f32_e32 v70, v94, v70
	v_exp_f32_e32 v40, v40
	v_add_f32_e32 v70, v70, v71
	v_mul_f32_e32 v134, v183, v186
	v_add_f32_e32 v183, v18, v70
	v_add_f32_e32 v32, 1.0, v32
	v_mul_f32_e32 v70, 0xbfb8aa3b, v183
	v_rcp_f32_e32 v32, v32
	v_exp_f32_e32 v70, v70
	v_add_f32_e32 v40, 1.0, v40
	v_rcp_f32_e32 v40, v40
	v_pk_mul_f32 v[94:95], v[116:117], v[68:69]
	v_lshlrev_b32_e32 v68, 16, v29
	v_lshlrev_b32_e32 v69, 16, v33
	v_mul_f32_e32 v186, v28, v32
	v_add_f32_e32 v28, 1.0, v70
	v_pk_mov_b32 v[70:71], v[138:139], v[68:69] op_sel:[1,0]
	v_pk_mul_f32 v[184:185], v[116:117], v[138:139]
	v_pk_mul_f32 v[138:139], v[88:89], v[70:71]
	v_add_f32_e32 v32, v94, v95
	v_mul_f32_e32 v187, v36, v40
	v_add_f32_e32 v32, v32, v138
	v_pk_mul_f32 v[94:95], v[88:89], v[68:69]
	v_add_f32_e32 v40, v184, v185
	v_add_f32_e32 v32, v32, v139
	v_add_f32_e32 v40, v40, v94
	v_add_f32_e32 v32, v18, v32
	v_add_f32_e32 v40, v40, v95
	v_mul_f32_e32 v36, 0xbfb8aa3b, v32
	v_add_f32_e32 v68, v18, v40
	v_exp_f32_e32 v36, v36
	v_mul_f32_e32 v40, 0xbfb8aa3b, v68
	v_exp_f32_e32 v40, v40
	v_and_b32_e32 v41, 0xffff0000, v41
	v_add_f32_e32 v36, 1.0, v36
	v_rcp_f32_e32 v94, v36
	v_add_f32_e32 v36, 1.0, v40
	v_and_b32_e32 v40, 0xffff0000, v37
	v_rcp_f32_e32 v95, v36
	v_pk_mov_b32 v[36:37], v[74:75], v[40:41] op_sel:[1,0]
	v_pk_mul_f32 v[82:83], v[14:15], v[74:75]
	v_pk_mul_f32 v[74:75], v[22:23], v[36:37]
	v_add_f32_e32 v86, v86, v87
	v_add_f32_e32 v74, v86, v74
	v_add_f32_e32 v74, v74, v75
	v_add_f32_e32 v86, v19, v74
	v_mul_f32_e32 v74, 0xbfb8aa3b, v86
	v_rcp_f32_e32 v28, v28
	v_exp_f32_e32 v74, v74
	v_mul_f32_e32 v68, v68, v95
	v_mul_f32_e32 v94, v32, v94
	v_mul_f32_e32 v87, v183, v28
	v_add_f32_e32 v28, 1.0, v74
	v_rcp_f32_e32 v95, v28
	v_pk_mul_f32 v[74:75], v[22:23], v[40:41]
	v_add_f32_e32 v28, v82, v83
	v_add_f32_e32 v28, v28, v74
	v_add_f32_e32 v28, v28, v75
	v_add_f32_e32 v82, v19, v28
	v_mul_f32_e32 v28, 0xbfb8aa3b, v82
	v_and_b32_e32 v33, 0xffff0000, v33
	v_and_b32_e32 v32, 0xffff0000, v29
	v_exp_f32_e32 v83, v28
	v_pk_mul_f32 v[36:37], v[14:15], v[36:37]
	v_pk_mov_b32 v[28:29], v[40:41], v[32:33] op_sel:[1,0]
	v_add_f32_e32 v36, v36, v37
	v_pk_mul_f32 v[74:75], v[22:23], v[28:29]
	v_mul_f32_e32 v86, v86, v95
	v_add_f32_e32 v36, v36, v74
	v_add_f32_e32 v36, v36, v75
	v_add_f32_e32 v74, v19, v36
	v_mul_f32_e32 v36, 0xbfb8aa3b, v74
	v_exp_f32_e32 v75, v36
	v_add_f32_e32 v36, 1.0, v83
	v_rcp_f32_e32 v83, v36
	v_pk_mul_f32 v[36:37], v[14:15], v[40:41]
	v_add_f32_e32 v40, 1.0, v75
	v_rcp_f32_e32 v75, v40
	v_pk_mul_f32 v[40:41], v[22:23], v[32:33]
	v_add_f32_e32 v32, v36, v37
	v_add_f32_e32 v32, v32, v40
	v_add_f32_e32 v32, v32, v41
	v_add_f32_e32 v32, v19, v32
	v_mul_f32_e32 v36, 0xbfb8aa3b, v32
	v_exp_f32_e32 v36, v36
	v_mul_f32_e32 v82, v82, v83
	v_mul_f32_e32 v83, v74, v75
	v_lshlrev_b32_e32 v75, 16, v42
; template <bool WITH_C, bool B_TR>
; __device__ __forceinline__ void ssd_stage(const Params& p, LAS unsigned char* lds, int b, int c, int g) {
;     ...
;         for (int hb = 0; hb < 2; ++hb) {
;             float y[8][8];
; #pragma unroll
;             for (int tt = 0; tt < 8; ++tt) {
;                 float u0[8]; unpack8(rows[3 + 8 * hb + tt], u0);
; #pragma unroll
;                 for (int i = 0; i < 8; ++i) { const float a = w0[i] * u3[i] + w1[i] * u2[i] + w2[i] * u1[i] + w3[i] * u0[i] + bs[i]; y[tt][i] = a * __builtin_amdgcn_rcpf(1.f + __expf(-a)); u3[i] = u2[i]; u2[i] = u1[i]; u1[i] = u0[i]; }
	v_add_f32_e32 v36, 1.0, v36
	v_lshlrev_b32_e32 v74, 16, v38
	v_rcp_f32_e32 v95, v36
	v_pk_mov_b32 v[36:37], v[66:67], v[74:75] op_sel:[1,0]
	v_pk_mul_f32 v[78:79], v[104:105], v[66:67]
	v_pk_mul_f32 v[40:41], v[90:91], v[36:37]
	v_add_f32_e32 v66, v80, v81
	v_add_f32_e32 v40, v66, v40
	v_add_f32_e32 v40, v40, v41
	v_add_f32_e32 v80, v4, v40
	v_mul_f32_e32 v40, 0xbfb8aa3b, v80
	v_exp_f32_e32 v66, v40
	v_pk_mul_f32 v[40:41], v[90:91], v[74:75]
	v_add_f32_e32 v67, v78, v79
	v_add_f32_e32 v40, v67, v40
	v_add_f32_e32 v40, v40, v41
	v_add_f32_e32 v81, v4, v40
	v_mul_f32_e32 v40, 0xbfb8aa3b, v81
	v_exp_f32_e32 v40, v40
	v_add_f32_e32 v41, 1.0, v66
	v_pk_mul_f32 v[66:67], v[104:105], v[36:37]
	v_lshlrev_b32_e32 v36, 16, v30
	v_add_f32_e32 v40, 1.0, v40
	v_lshlrev_b32_e32 v37, 16, v34
	v_mul_f32_e32 v54, v54, v135
	v_mul_f32_e32 v32, v32, v95
	v_rcp_f32_e32 v95, v41
	v_rcp_f32_e32 v135, v40
	v_pk_mov_b32 v[40:41], v[74:75], v[36:37] op_sel:[1,0]
	v_add_f32_e32 v66, v66, v67
	v_pk_mul_f32 v[78:79], v[90:91], v[40:41]
	v_mul_f32_e32 v80, v80, v95
	v_add_f32_e32 v66, v66, v78
	v_add_f32_e32 v66, v66, v79
	v_add_f32_e32 v78, v4, v66
	v_mul_f32_e32 v66, 0xbfb8aa3b, v78
	v_exp_f32_e32 v79, v66
	v_pk_mul_f32 v[66:67], v[104:105], v[74:75]
	v_pk_mul_f32 v[74:75], v[90:91], v[36:37]
	v_add_f32_e32 v36, v66, v67
	v_add_f32_e32 v36, v36, v74
	v_add_f32_e32 v36, v36, v75
	v_add_f32_e32 v36, v4, v36
	v_mul_f32_e32 v66, 0xbfb8aa3b, v36
	v_exp_f32_e32 v95, v66
	v_and_b32_e32 v67, 0xffff0000, v42
	v_and_b32_e32 v66, 0xffff0000, v38
	v_pk_mul_f32 v[76:77], v[0:1], v[60:61]
	v_pk_mov_b32 v[60:61], v[60:61], v[66:67] op_sel:[1,0]
	v_add_f32_e32 v38, v72, v73
	v_pk_mul_f32 v[74:75], v[8:9], v[60:61]
	v_add_f32_e32 v72, 1.0, v95
	v_add_f32_e32 v38, v38, v74
	v_add_f32_e32 v38, v38, v75
	v_add_f32_e32 v38, v5, v38
	v_mul_f32_e32 v42, 0xbfb8aa3b, v38
	v_exp_f32_e32 v42, v42
	v_rcp_f32_e32 v75, v72
	v_pk_mul_f32 v[72:73], v[8:9], v[66:67]
	v_add_f32_e32 v76, v76, v77
	v_add_f32_e32 v72, v76, v72
	v_add_f32_e32 v79, 1.0, v79
	v_add_f32_e32 v72, v72, v73
	v_rcp_f32_e32 v74, v79
	v_add_f32_e32 v79, v5, v72
	v_add_f32_e32 v42, 1.0, v42
	v_mul_f32_e32 v72, 0xbfb8aa3b, v79
	v_rcp_f32_e32 v42, v42
	v_exp_f32_e32 v72, v72
	v_mul_f32_e32 v78, v78, v74
	v_mul_f32_e32 v36, v36, v75
	v_mul_f32_e32 v95, v38, v42
	v_add_f32_e32 v38, 1.0, v72
	v_pk_mul_f32 v[60:61], v[0:1], v[60:61]
	v_pk_mul_f32 v[72:73], v[0:1], v[66:67]
	v_and_b32_e32 v75, 0xffff0000, v34
	v_and_b32_e32 v74, 0xffff0000, v30
	v_add_f32_e32 v30, v60, v61
	v_pk_mul_f32 v[60:61], v[8:9], v[74:75]
	v_add_f32_e32 v42, v72, v73
	v_add_f32_e32 v42, v42, v60
	v_add_f32_e32 v42, v42, v61
	v_add_f32_e32 v42, v5, v42
	v_mul_f32_e32 v60, 0xbfb8aa3b, v42
	v_exp_f32_e32 v60, v60
	v_pk_mov_b32 v[66:67], v[66:67], v[74:75] op_sel:[1,0]
	v_lshlrev_b32_e32 v61, 16, v43
	v_pk_mul_f32 v[76:77], v[8:9], v[66:67]
	v_add_f32_e32 v60, 1.0, v60
	v_add_f32_e32 v30, v30, v76
	v_add_f32_e32 v30, v30, v77
	v_add_f32_e32 v30, v5, v30
	v_rcp_f32_e32 v74, v60
	v_lshlrev_b32_e32 v60, 16, v39
	v_pk_mul_f32 v[62:63], v[96:97], v[52:53]
	v_mul_f32_e32 v34, 0xbfb8aa3b, v30
	v_pk_mov_b32 v[52:53], v[52:53], v[60:61] op_sel:[1,0]
	v_exp_f32_e32 v34, v34
	v_pk_mul_f32 v[72:73], v[84:85], v[52:53]
	v_add_f32_e32 v64, v64, v65
	v_add_f32_e32 v64, v64, v72
	v_add_f32_e32 v64, v64, v73
	v_add_f32_e32 v76, v6, v64
	v_add_f32_e32 v34, 1.0, v34
	v_mul_f32_e32 v64, 0xbfb8aa3b, v76
	v_rcp_f32_e32 v38, v38
	v_rcp_f32_e32 v34, v34
	v_exp_f32_e32 v64, v64
	v_pk_mul_f32 v[52:53], v[96:97], v[52:53]
	v_mul_f32_e32 v77, v79, v38
	v_mul_f32_e32 v79, v30, v34
	v_add_f32_e32 v30, 1.0, v64
	v_pk_mul_f32 v[64:65], v[84:85], v[60:61]
	v_add_f32_e32 v34, v62, v63
	v_add_f32_e32 v34, v34, v64
	v_lshlrev_b32_e32 v62, 16, v31
	v_lshlrev_b32_e32 v63, 16, v35
	v_add_f32_e32 v34, v34, v65
	v_pk_mov_b32 v[64:65], v[60:61], v[62:63] op_sel:[1,0]
	v_mul_f32_e32 v74, v42, v74
	v_pk_mul_f32 v[72:73], v[84:85], v[64:65]
	v_add_f32_e32 v42, v52, v53
	v_add_f32_e32 v42, v42, v72
	v_add_f32_e32 v42, v42, v73
	v_add_f32_e32 v42, v6, v42
	v_add_f32_e32 v34, v6, v34
	v_mul_f32_e32 v52, 0xbfb8aa3b, v42
	v_mul_f32_e32 v38, 0xbfb8aa3b, v34
	v_exp_f32_e32 v72, v52
	v_exp_f32_e32 v38, v38
	v_pk_mul_f32 v[52:53], v[96:97], v[60:61]
	v_and_b32_e32 v43, 0xffff0000, v43
	v_add_f32_e32 v60, 1.0, v72
	v_add_f32_e32 v38, 1.0, v38
	v_rcp_f32_e32 v72, v60
	v_pk_mul_f32 v[60:61], v[84:85], v[62:63]
	v_add_f32_e32 v52, v52, v53
	v_rcp_f32_e32 v38, v38
	v_add_f32_e32 v52, v52, v60
	v_add_f32_e32 v52, v52, v61
	v_add_f32_e32 v52, v6, v52
	v_mul_f32_e32 v53, 0xbfb8aa3b, v52
	v_mul_f32_e32 v62, v42, v72
	v_and_b32_e32 v42, 0xffff0000, v39
	v_rcp_f32_e32 v30, v30
	v_exp_f32_e32 v53, v53
	v_mul_f32_e32 v61, v34, v38
	v_pk_mov_b32 v[38:39], v[48:49], v[42:43] op_sel:[1,0]
	v_pk_mul_f32 v[50:51], v[2:3], v[48:49]
	v_pk_mul_f32 v[48:49], v[10:11], v[38:39]
	v_add_f32_e32 v34, v56, v57
	v_add_f32_e32 v34, v34, v48
	v_add_f32_e32 v34, v34, v49
	v_pk_mul_f32 v[48:49], v[10:11], v[42:43]
	v_add_f32_e32 v50, v50, v51
	v_mul_f32_e32 v60, v76, v30
	v_add_f32_e32 v30, 1.0, v53
	v_add_f32_e32 v53, v7, v34
	v_add_f32_e32 v48, v50, v48
	v_mul_f32_e32 v34, 0xbfb8aa3b, v53
	v_add_f32_e32 v48, v48, v49
	v_rcp_f32_e32 v30, v30
	v_exp_f32_e32 v34, v34
	v_add_f32_e32 v50, v7, v48
	v_mul_f32_e32 v48, 0xbfb8aa3b, v50
	v_exp_f32_e32 v48, v48
	v_mul_f32_e32 v52, v52, v30
	v_add_f32_e32 v30, 1.0, v34
	v_and_b32_e32 v35, 0xffff0000, v35
	v_and_b32_e32 v34, 0xffff0000, v31
	v_rcp_f32_e32 v51, v30
	v_pk_mul_f32 v[38:39], v[2:3], v[38:39]
	v_pk_mov_b32 v[30:31], v[42:43], v[34:35] op_sel:[1,0]
	v_add_f32_e32 v56, 1.0, v48
	v_pk_mul_f32 v[48:49], v[2:3], v[42:43]
	v_pk_mul_f32 v[42:43], v[10:11], v[30:31]
	v_add_f32_e32 v38, v38, v39
	v_add_f32_e32 v38, v38, v42
	v_add_f32_e32 v38, v38, v43
	v_add_f32_e32 v42, v7, v38
	v_mul_f32_e32 v38, 0xbfb8aa3b, v42
	v_exp_f32_e32 v43, v38
	v_pk_mul_f32 v[38:39], v[10:11], v[34:35]
	v_add_f32_e32 v34, v48, v49
	v_add_f32_e32 v34, v34, v38
	v_add_f32_e32 v34, v34, v39
	v_add_f32_e32 v34, v7, v34
	v_mul_f32_e32 v38, 0xbfb8aa3b, v34
	v_exp_f32_e32 v38, v38
	v_rcp_f32_e32 v39, v56
	v_add_f32_e32 v43, 1.0, v43
	v_rcp_f32_e32 v43, v43
	v_add_f32_e32 v38, 1.0, v38
	v_rcp_f32_e32 v38, v38
	v_mul_f32_e32 v56, v50, v39
	s_waitcnt vmcnt(0)
; #define LAS __attribute__((address_space(3)))
; __device__ __forceinline__ unsigned cvt_pk_bf16(float lo, float hi) { unsigned r; asm volatile("v_cvt_pk_bf16_f32 %0, %1, %2" : "=v"(r) : "v"(lo), "v"(hi)); return r; }
; template <bool WITH_C, bool B_TR>
; __device__ __forceinline__ void ssd_stage(const Params& p, LAS unsigned char* lds, int b, int c, int g) {
;     ...
;                 for (int i = 0; i < 8; ++i) { const float a = w0[i] * u3[i] + w1[i] * u2[i] + w2[i] * u1[i] + w3[i] * u0[i] + bs[i]; y[tt][i] = a * __builtin_amdgcn_rcpf(1.f + __expf(-a)); u3[i] = u2[i]; u2[i] = u1[i]; u1[i] = u0[i]; }
;             }
;             const bool tr = (kind == 0) || (kind == 1 && B_TR);
;             if (tr) {
;                 LAS unsigned char* img = lds + (kind == 0 ? SSD_XT : SSD_B);
;                 const int r0 = kind == 0 ? 8 * cg : 8 * (cg - 64);
; #pragma unroll
;                 for (int i = 0; i < 8; ++i) { u32x4 w; w.x = pg8::cvt_pk_bf16(y[0][i], y[1][i]); w.y = pg8::cvt_pk_bf16(y[2][i], y[3][i]); w.z = pg8::cvt_pk_bf16(y[4][i], y[5][i]); w.w = pg8::cvt_pk_bf16(y[6][i], y[7][i]);
;                     *(LAS u32x4*)(img + ((r0 + i) * 72 + 16 * seg + 8 * hb) * 2) = w; }
	v_lshlrev_b32_e32 v39, 16, v24
	v_pk_mul_f32 v[46:47], v[118:119], v[46:47]
	v_mul_f32_e32 v34, v34, v38
	v_mov_b32_e32 v38, v45
	v_mul_f32_e32 v57, v42, v43
	v_and_b32_e32 v43, 0xffff0000, v24
	v_pk_mul_f32 v[38:39], v[106:107], v[38:39]
	v_add_f32_e32 v24, v46, v47
	v_add_f32_e32 v24, v24, v38
	v_add_f32_e32 v24, v24, v39
	v_pk_mul_f32 v[12:13], v[12:13], v[58:59]
	v_mov_b32_e32 v42, v55
	v_add_f32_e32 v38, v16, v24
	v_pk_mul_f32 v[20:21], v[20:21], v[42:43]
	v_add_f32_e32 v12, v12, v13
	v_mul_f32_e32 v16, 0xbfb8aa3b, v38
	v_add_f32_e32 v12, v12, v20
	v_exp_f32_e32 v16, v16
	v_add_f32_e32 v12, v12, v21
	v_add_f32_e32 v20, v17, v12
	v_mul_f32_e32 v12, 0xbfb8aa3b, v20
	v_lshlrev_b32_e32 v49, 16, v25
	v_exp_f32_e32 v21, v12
	v_pk_mul_f32 v[12:13], v[116:117], v[70:71]
	v_mov_b32_e32 v48, v69
	v_add_f32_e32 v24, 1.0, v16
	v_pk_mul_f32 v[16:17], v[88:89], v[48:49]
	v_add_f32_e32 v12, v12, v13
	v_add_f32_e32 v12, v12, v16
	v_add_f32_e32 v12, v12, v17
	v_add_f32_e32 v16, v18, v12
	v_mul_f32_e32 v12, 0xbfb8aa3b, v16
	v_exp_f32_e32 v12, v12
	v_add_f32_e32 v13, 1.0, v21
	v_and_b32_e32 v25, 0xffff0000, v25
	v_rcp_f32_e32 v17, v24
	v_add_f32_e32 v12, 1.0, v12
	v_rcp_f32_e32 v18, v13
	v_rcp_f32_e32 v21, v12
	v_pk_mul_f32 v[12:13], v[14:15], v[28:29]
	v_mov_b32_e32 v24, v33
	v_pk_mul_f32 v[14:15], v[22:23], v[24:25]
	v_add_f32_e32 v12, v12, v13
	v_add_f32_e32 v12, v12, v14
	v_add_f32_e32 v12, v12, v15
	v_add_f32_e32 v19, v19, v12
	v_mul_f32_e32 v12, 0xbfb8aa3b, v19
	v_exp_f32_e32 v12, v12
	v_mul_f32_e32 v53, v53, v51
	v_lshlrev_b32_e32 v51, 16, v26
	v_mul_f32_e32 v18, v20, v18
	v_add_f32_e32 v12, 1.0, v12
	v_rcp_f32_e32 v20, v12
	v_pk_mul_f32 v[12:13], v[104:105], v[40:41]
	v_mov_b32_e32 v50, v37
	v_and_b32_e32 v39, 0xffff0000, v26
	v_mul_f32_e32 v17, v38, v17
	v_pk_mul_f32 v[14:15], v[90:91], v[50:51]
	v_add_f32_e32 v12, v12, v13
	v_pk_mul_f32 v[0:1], v[0:1], v[66:67]
	v_mov_b32_e32 v38, v75
	v_add_f32_e32 v12, v12, v14
	v_pk_mul_f32 v[8:9], v[8:9], v[38:39]
	v_add_f32_e32 v0, v0, v1
	v_add_f32_e32 v12, v12, v15
	v_add_f32_e32 v0, v0, v8
	v_add_f32_e32 v12, v4, v12
	v_add_f32_e32 v0, v0, v9
	v_mul_f32_e32 v4, 0xbfb8aa3b, v12
	v_add_f32_e32 v8, v5, v0
	v_exp_f32_e32 v4, v4
	v_mul_f32_e32 v0, 0xbfb8aa3b, v8
	v_exp_f32_e32 v0, v0
	v_lshlrev_b32_e32 v47, 16, v27
	v_add_f32_e32 v1, 1.0, v4
	v_rcp_f32_e32 v13, v1
	v_add_f32_e32 v14, 1.0, v0
	v_pk_mul_f32 v[0:1], v[96:97], v[64:65]
	v_mov_b32_e32 v46, v63
	v_pk_mul_f32 v[4:5], v[84:85], v[46:47]
	v_add_f32_e32 v0, v0, v1
	v_add_f32_e32 v0, v0, v4
	v_add_f32_e32 v0, v0, v5
	v_add_f32_e32 v4, v6, v0
	v_mul_f32_e32 v0, 0xbfb8aa3b, v4
	v_and_b32_e32 v27, 0xffff0000, v27
	v_exp_f32_e32 v5, v0
	v_pk_mul_f32 v[0:1], v[2:3], v[30:31]
	v_mov_b32_e32 v26, v35
	v_pk_mul_f32 v[2:3], v[10:11], v[26:27]
	v_add_f32_e32 v0, v0, v1
	v_add_f32_e32 v0, v0, v2
	v_add_f32_e32 v0, v0, v3
	v_add_f32_e32 v0, v7, v0
	v_mul_f32_e32 v1, 0xbfb8aa3b, v0
	v_exp_f32_e32 v1, v1
	v_add_f32_e32 v3, 1.0, v5
	v_rcp_f32_e32 v2, v14
	v_rcp_f32_e32 v3, v3
	v_add_f32_e32 v1, 1.0, v1
	v_rcp_f32_e32 v1, v1
	v_mul_f32_e32 v6, v8, v2
	v_mul_f32_e32 v4, v4, v3
	v_mul_f32_e32 v16, v16, v21
	v_mul_f32_e32 v7, v0, v1
	v_cvt_pk_bf16_f32 v0, v121, v100
	v_cvt_pk_bf16_f32 v1, v101, v44
	v_cvt_pk_bf16_f32 v2, v93, v131
	v_cvt_pk_bf16_f32 v3, v132, v17
	ds_write_b128 v115, v[0:3] offset:16
	v_cvt_pk_bf16_f32 v0, v120, v102
	v_cvt_pk_bf16_f32 v1, v109, v133
	v_cvt_pk_bf16_f32 v2, v134, v186
	v_cvt_pk_bf16_f32 v3, v187, v18
	ds_write_b128 v114, v[0:3] offset:160
	v_cvt_pk_bf16_f32 v0, v122, v103
	v_cvt_pk_bf16_f32 v1, v108, v54
	v_cvt_pk_bf16_f32 v2, v87, v94
	v_cvt_pk_bf16_f32 v3, v68, v16
	ds_write_b128 v114, v[0:3] offset:304
	v_cvt_pk_bf16_f32 v0, v123, v126
	v_cvt_pk_bf16_f32 v1, v127, v86
	v_mul_f32_e32 v9, v19, v20
	v_cvt_pk_bf16_f32 v2, v82, v83
	v_cvt_pk_bf16_f32 v3, v32, v9
	ds_write_b128 v114, v[0:3] offset:448
	v_cvt_pk_bf16_f32 v0, v124, v128
	v_cvt_pk_bf16_f32 v1, v129, v80
	v_mul_f32_e32 v81, v81, v135
	v_mul_f32_e32 v5, v12, v13
	v_cvt_pk_bf16_f32 v2, v81, v78
	v_cvt_pk_bf16_f32 v3, v36, v5
	ds_write_b128 v114, v[0:3] offset:592
	v_cvt_pk_bf16_f32 v0, v125, v110
	v_cvt_pk_bf16_f32 v1, v111, v95
	v_cvt_pk_bf16_f32 v2, v77, v79
	v_cvt_pk_bf16_f32 v3, v74, v6
	ds_write_b128 v114, v[0:3] offset:736
	v_cvt_pk_bf16_f32 v0, v112, v98
	v_cvt_pk_bf16_f32 v1, v99, v60
	v_cvt_pk_bf16_f32 v2, v61, v62
	v_cvt_pk_bf16_f32 v3, v52, v4
	ds_write_b128 v114, v[0:3] offset:880
	v_cvt_pk_bf16_f32 v0, v113, v130
	v_cvt_pk_bf16_f32 v1, v92, v53
	v_cvt_pk_bf16_f32 v2, v56, v57
	v_cvt_pk_bf16_f32 v3, v34, v7
	ds_write_b128 v114, v[0:3] offset:1024
	v_mov_b64_e32 v[138:139], s[18:19]
	v_mov_b64_e32 v[0:1], s[22:23]
	v_mov_b32_e32 v4, s35
